# scan step reordered for longer distances between dependent packed/DPP ops (same 40 instructions), X=10
# speedup vs baseline: 1.0020x; 1.0020x over previous
; #define LAS __attribute__((address_space(3)))
; template <int CTRL> __device__ __forceinline__ float dppf(float x) { return __builtin_bit_cast(float, __builtin_amdgcn_mov_dpp(__builtin_bit_cast(int, x), CTRL, 0xf, 0xf, true)); }
; __device__ __forceinline__ void rwkv_item(LAS unsigned char* lds, int l, const bf16_t* PROJ, const bf16_t* LO, bf16_t* YR, float* BON, int b, int h, int qv) {
;     ...
;         for (int ci = 0; ci < NCH; ++ci) {
;             const LAS float* pk = base + (ci & 1) * BUFF + 4 * kq; const LAS float* pv = base + (ci & 1) * BUFF + 10240 + rl; const LAS float* ps = base + (ci & 1) * BUFF + 11264;
;             LAS float* py = yA + (ci & 1) * 4096 + rl * 4 + (kq >> 2);
;             f32x4 kk4 = *(const LAS f32x4*)(pk), wr4 = *(const LAS f32x4*)(pk + 2048), w4 = *(const LAS f32x4*)(pk + 4096), k4 = *(const LAS f32x4*)(pk + 6144), a4 = *(const LAS f32x4*)(pk + 8192);
;             float vv[2] = {pv[0], pv[4]}; f32x2 sc = *(const LAS f32x2*)(ps);
; #pragma unroll 32
;             for (int t = 0; t < CH; ++t) {
;                 const int tn = (t + 1) & (CH - 1);
;                 const LAS float* pn = pk + tn * 64;
;                 const f32x4 nkk = *(const LAS f32x4*)(pn), nwr = *(const LAS f32x4*)(pn + 2048), nw = *(const LAS f32x4*)(pn + 4096), nk = *(const LAS f32x4*)(pn + 6144), na = *(const LAS f32x4*)(pn + 8192);
;                 const float nv0 = pv[tn * 32], nv1 = pv[tn * 32 + 4]; const f32x2 nsc = *(const LAS f32x2*)(ps + 2 * tn);
;                 float sa[2], yp[2];
; #pragma unroll
;                 for (int c = 0; c < 2; ++c) { const f32x2 pa = S23[c] * kk4.hi + S01[c] * kk4.lo, pb = S23[c] * wr4.hi + S01[c] * wr4.lo; sa[c] = pa.x + pa.y; yp[c] = pb.x + pb.y; }
; #pragma unroll
;                 for (int c = 0; c < 2; ++c) { sa[c] = sum16(sa[c]); yp[c] += dppf<0xB1>(yp[c]); yp[c] += dppf<0x4E>(yp[c]); }
; #pragma unroll
;                 for (int c = 0; c < 2; ++c) {
;                     S01[c] = S01[c] * w4.lo + (k4.lo * vv[c] - a4.lo * sa[c]);
;                     S23[c] = S23[c] * w4.hi + (k4.hi * vv[c] - a4.hi * sa[c]);
;                     py[(t * 32 + 4 * c) * 4] = yp[c] + 0.25f * (vv[c] * sc.x - sa[c] * sc.y);
;                 }
;                 kk4 = nkk; wr4 = nwr; w4 = nw; k4 = nk; a4 = na; vv[0] = nv0; vv[1] = nv1; sc = nsc;
;             }
.Lscan_chunk:
	s_and_b32 s24, s30, 1
	s_mul_i32 s4, s24, 0xb200
	s_lshl_b32 s31, s24, 14
	v_add_u32_e32 v10, s4, v84
	v_add_u32_e32 v11, s4, v85
	v_add_u32_e32 v12, s4, v86
	v_mov_b32_e32 v13, s4
	v_add_u32_e32 v14, s31, v87
	ds_read_b128 v[16:19], v10 offset:0
	ds_read_b128 v[20:23], v10 offset:8192
	ds_read_b128 v[24:27], v10 offset:16384
	ds_read_b128 v[28:31], v10 offset:24576
	ds_read_b128 v[32:35], v10 offset:32768
	ds_read_b32 v36, v11 offset:40960
	ds_read_b32 v37, v12 offset:40960
	ds_read_b64 v[38:39], v13 offset:45056
	s_waitcnt lgkmcnt(0)
	s_waitcnt lgkmcnt(1)
	v_pk_mul_f32 v[64:65], v[2:3], v[16:17] op_sel_hi:[1,0]
	v_pk_mul_f32 v[66:67], v[2:3], v[20:21] op_sel_hi:[1,0]
	v_pk_mul_f32 v[68:69], v[36:37], v[28:29] op_sel_hi:[1,0]
	v_pk_fma_f32 v[64:65], v[4:5], v[16:17], v[64:65] op_sel:[0,1,0] op_sel_hi:[1,1,1]
	v_pk_fma_f32 v[66:67], v[4:5], v[20:21], v[66:67] op_sel:[0,1,0] op_sel_hi:[1,1,1]
	v_pk_mul_f32 v[70:71], v[36:37], v[28:29] op_sel:[0,1] op_sel_hi:[1,1]
	v_pk_fma_f32 v[64:65], v[6:7], v[18:19], v[64:65] op_sel_hi:[1,0,1]
	v_pk_fma_f32 v[66:67], v[6:7], v[22:23], v[66:67] op_sel_hi:[1,0,1]
	v_pk_mul_f32 v[72:73], v[36:37], v[30:31] op_sel_hi:[1,0]
	v_pk_fma_f32 v[64:65], v[8:9], v[18:19], v[64:65] op_sel:[0,1,0] op_sel_hi:[1,1,1]
	v_pk_fma_f32 v[66:67], v[8:9], v[22:23], v[66:67] op_sel:[0,1,0] op_sel_hi:[1,1,1]
	v_pk_mul_f32 v[74:75], v[36:37], v[30:31] op_sel:[0,1] op_sel_hi:[1,1]
	ds_read_b128 v[40:43], v10 offset:256
	v_add_f32_dpp v78, v65, v64 quad_perm:[1,0,3,2] row_mask:0xf bank_mask:0xf bound_ctrl:1
	ds_read_b128 v[44:47], v10 offset:8448
	ds_read_b128 v[48:51], v10 offset:16640
	v_pk_fma_f32 v[68:69], v[2:3], v[24:25], v[68:69] op_sel_hi:[1,0,1]
	v_add_f32_dpp v79, v78, v78 quad_perm:[3,2,1,0] row_mask:0xf bank_mask:0xf bound_ctrl:1
	ds_read_b128 v[52:55], v10 offset:24832
	ds_read_b128 v[56:59], v10 offset:33024
	v_pk_fma_f32 v[70:71], v[4:5], v[24:25], v[70:71] op_sel:[0,1,0] op_sel_hi:[1,1,1]
	v_add_f32_dpp v80, v79, v79 row_half_mirror row_mask:0xf bank_mask:0xf bound_ctrl:1
	ds_read_b32 v60, v11 offset:41088
	ds_read_b32 v61, v12 offset:41088
	v_pk_fma_f32 v[72:73], v[6:7], v[26:27], v[72:73] op_sel_hi:[1,0,1]
	v_add_f32_dpp v76, v80, v80 row_mirror row_mask:0xf bank_mask:0xf bound_ctrl:1
	ds_read_b64 v[62:63], v13 offset:45064
	v_pk_fma_f32 v[74:75], v[8:9], v[26:27], v[74:75] op_sel:[0,1,0] op_sel_hi:[1,1,1]
	v_mul_f32_e32 v83, v36, v38
	v_mov_b32_dpp v77, v76 quad_perm:[1,0,3,2] row_mask:0xf bank_mask:0xf bound_ctrl:1
	v_add_f32_dpp v81, v67, v66 quad_perm:[1,0,3,2] row_mask:0xf bank_mask:0xf bound_ctrl:1
	v_pk_fma_f32 v[2:3], v[32:33], v[76:77], v[68:69] op_sel_hi:[0,1,1] neg_lo:[1,0,0] neg_hi:[1,0,0]
	v_pk_fma_f32 v[4:5], v[32:33], v[76:77], v[70:71] op_sel:[1,0,0] op_sel_hi:[1,1,1] neg_lo:[1,0,0] neg_hi:[1,0,0]
	v_pk_fma_f32 v[6:7], v[34:35], v[76:77], v[72:73] op_sel_hi:[0,1,1] neg_lo:[1,0,0] neg_hi:[1,0,0]
	v_pk_fma_f32 v[8:9], v[34:35], v[76:77], v[74:75] op_sel:[1,0,0] op_sel_hi:[1,1,1] neg_lo:[1,0,0] neg_hi:[1,0,0]
	v_fma_f32 v83, -v76, v39, v83
	v_add_f32_dpp v82, v81, v81 quad_perm:[3,2,1,0] row_mask:0xf bank_mask:0xf bound_ctrl:1
	v_fmac_f32_e32 v82, 0x3e800000, v83
	ds_write_b32 v14, v82 offset:0
	s_waitcnt lgkmcnt(1)
	v_pk_mul_f32 v[64:65], v[2:3], v[40:41] op_sel_hi:[1,0]
	v_pk_mul_f32 v[66:67], v[2:3], v[44:45] op_sel_hi:[1,0]
	v_pk_mul_f32 v[68:69], v[60:61], v[52:53] op_sel_hi:[1,0]
	v_pk_fma_f32 v[64:65], v[4:5], v[40:41], v[64:65] op_sel:[0,1,0] op_sel_hi:[1,1,1]
	v_pk_fma_f32 v[66:67], v[4:5], v[44:45], v[66:67] op_sel:[0,1,0] op_sel_hi:[1,1,1]
	v_pk_mul_f32 v[70:71], v[60:61], v[52:53] op_sel:[0,1] op_sel_hi:[1,1]
	v_pk_fma_f32 v[64:65], v[6:7], v[42:43], v[64:65] op_sel_hi:[1,0,1]
	v_pk_fma_f32 v[66:67], v[6:7], v[46:47], v[66:67] op_sel_hi:[1,0,1]
	v_pk_mul_f32 v[72:73], v[60:61], v[54:55] op_sel_hi:[1,0]
	v_pk_fma_f32 v[64:65], v[8:9], v[42:43], v[64:65] op_sel:[0,1,0] op_sel_hi:[1,1,1]
	v_pk_fma_f32 v[66:67], v[8:9], v[46:47], v[66:67] op_sel:[0,1,0] op_sel_hi:[1,1,1]
	v_pk_mul_f32 v[74:75], v[60:61], v[54:55] op_sel:[0,1] op_sel_hi:[1,1]
	ds_read_b128 v[16:19], v10 offset:512
	v_add_f32_dpp v78, v65, v64 quad_perm:[1,0,3,2] row_mask:0xf bank_mask:0xf bound_ctrl:1
	ds_read_b128 v[20:23], v10 offset:8704
	ds_read_b128 v[24:27], v10 offset:16896
	v_pk_fma_f32 v[68:69], v[2:3], v[48:49], v[68:69] op_sel_hi:[1,0,1]
	v_add_f32_dpp v79, v78, v78 quad_perm:[3,2,1,0] row_mask:0xf bank_mask:0xf bound_ctrl:1
	ds_read_b128 v[28:31], v10 offset:25088
	ds_read_b128 v[32:35], v10 offset:33280
	v_pk_fma_f32 v[70:71], v[4:5], v[48:49], v[70:71] op_sel:[0,1,0] op_sel_hi:[1,1,1]
	v_add_f32_dpp v80, v79, v79 row_half_mirror row_mask:0xf bank_mask:0xf bound_ctrl:1
	ds_read_b32 v36, v11 offset:41216
	ds_read_b32 v37, v12 offset:41216
	v_pk_fma_f32 v[72:73], v[6:7], v[50:51], v[72:73] op_sel_hi:[1,0,1]
	v_add_f32_dpp v76, v80, v80 row_mirror row_mask:0xf bank_mask:0xf bound_ctrl:1
	ds_read_b64 v[38:39], v13 offset:45072
	v_pk_fma_f32 v[74:75], v[8:9], v[50:51], v[74:75] op_sel:[0,1,0] op_sel_hi:[1,1,1]
	v_mul_f32_e32 v83, v60, v62
	v_mov_b32_dpp v77, v76 quad_perm:[1,0,3,2] row_mask:0xf bank_mask:0xf bound_ctrl:1
	v_add_f32_dpp v81, v67, v66 quad_perm:[1,0,3,2] row_mask:0xf bank_mask:0xf bound_ctrl:1
	v_pk_fma_f32 v[2:3], v[56:57], v[76:77], v[68:69] op_sel_hi:[0,1,1] neg_lo:[1,0,0] neg_hi:[1,0,0]
	v_pk_fma_f32 v[4:5], v[56:57], v[76:77], v[70:71] op_sel:[1,0,0] op_sel_hi:[1,1,1] neg_lo:[1,0,0] neg_hi:[1,0,0]
	v_pk_fma_f32 v[6:7], v[58:59], v[76:77], v[72:73] op_sel_hi:[0,1,1] neg_lo:[1,0,0] neg_hi:[1,0,0]
	v_pk_fma_f32 v[8:9], v[58:59], v[76:77], v[74:75] op_sel:[1,0,0] op_sel_hi:[1,1,1] neg_lo:[1,0,0] neg_hi:[1,0,0]
	v_fma_f32 v83, -v76, v63, v83
	v_add_f32_dpp v82, v81, v81 quad_perm:[3,2,1,0] row_mask:0xf bank_mask:0xf bound_ctrl:1
	v_fmac_f32_e32 v82, 0x3e800000, v83
	ds_write_b32 v14, v82 offset:512
	s_waitcnt lgkmcnt(1)
; #define LAS __attribute__((address_space(3)))
; template <int CTRL> __device__ __forceinline__ float dppf(float x) { return __builtin_bit_cast(float, __builtin_amdgcn_mov_dpp(__builtin_bit_cast(int, x), CTRL, 0xf, 0xf, true)); }
; __device__ __forceinline__ float sum16(float x) { x = sum8(x); x += dppf<0x140>(x); return x; }
; __device__ __forceinline__ void rwkv_item(LAS unsigned char* lds, int l, const bf16_t* PROJ, const bf16_t* LO, bf16_t* YR, float* BON, int b, int h, int qv) {
;     ...
;             for (int t = 0; t < CH; ++t) {
;                 const int tn = (t + 1) & (CH - 1);
;                 const LAS float* pn = pk + tn * 64;
;                 const f32x4 nkk = *(const LAS f32x4*)(pn), nwr = *(const LAS f32x4*)(pn + 2048), nw = *(const LAS f32x4*)(pn + 4096), nk = *(const LAS f32x4*)(pn + 6144), na = *(const LAS f32x4*)(pn + 8192);
;                 const float nv0 = pv[tn * 32], nv1 = pv[tn * 32 + 4]; const f32x2 nsc = *(const LAS f32x2*)(ps + 2 * tn);
;                 float sa[2], yp[2];
; #pragma unroll
;                 for (int c = 0; c < 2; ++c) { const f32x2 pa = S23[c] * kk4.hi + S01[c] * kk4.lo, pb = S23[c] * wr4.hi + S01[c] * wr4.lo; sa[c] = pa.x + pa.y; yp[c] = pb.x + pb.y; }
; #pragma unroll
;                 for (int c = 0; c < 2; ++c) { sa[c] = sum16(sa[c]); yp[c] += dppf<0xB1>(yp[c]); yp[c] += dppf<0x4E>(yp[c]); }
; #pragma unroll
;                 for (int c = 0; c < 2; ++c) {
;                     S01[c] = S01[c] * w4.lo + (k4.lo * vv[c] - a4.lo * sa[c]);
;                     S23[c] = S23[c] * w4.hi + (k4.hi * vv[c] - a4.hi * sa[c]);
;                     py[(t * 32 + 4 * c) * 4] = yp[c] + 0.25f * (vv[c] * sc.x - sa[c] * sc.y);
;                 }
;                 kk4 = nkk; wr4 = nwr; w4 = nw; k4 = nk; a4 = na; vv[0] = nv0; vv[1] = nv1; sc = nsc;
;             }
	v_pk_mul_f32 v[64:65], v[2:3], v[16:17] op_sel_hi:[1,0]
	v_pk_mul_f32 v[66:67], v[2:3], v[20:21] op_sel_hi:[1,0]
	v_pk_mul_f32 v[68:69], v[36:37], v[28:29] op_sel_hi:[1,0]
	v_pk_fma_f32 v[64:65], v[4:5], v[16:17], v[64:65] op_sel:[0,1,0] op_sel_hi:[1,1,1]
	v_pk_fma_f32 v[66:67], v[4:5], v[20:21], v[66:67] op_sel:[0,1,0] op_sel_hi:[1,1,1]
	v_pk_mul_f32 v[70:71], v[36:37], v[28:29] op_sel:[0,1] op_sel_hi:[1,1]
	v_pk_fma_f32 v[64:65], v[6:7], v[18:19], v[64:65] op_sel_hi:[1,0,1]
	v_pk_fma_f32 v[66:67], v[6:7], v[22:23], v[66:67] op_sel_hi:[1,0,1]
	v_pk_mul_f32 v[72:73], v[36:37], v[30:31] op_sel_hi:[1,0]
	v_pk_fma_f32 v[64:65], v[8:9], v[18:19], v[64:65] op_sel:[0,1,0] op_sel_hi:[1,1,1]
	v_pk_fma_f32 v[66:67], v[8:9], v[22:23], v[66:67] op_sel:[0,1,0] op_sel_hi:[1,1,1]
	v_pk_mul_f32 v[74:75], v[36:37], v[30:31] op_sel:[0,1] op_sel_hi:[1,1]
	ds_read_b128 v[40:43], v10 offset:768
	v_add_f32_dpp v78, v65, v64 quad_perm:[1,0,3,2] row_mask:0xf bank_mask:0xf bound_ctrl:1
	ds_read_b128 v[44:47], v10 offset:8960
	ds_read_b128 v[48:51], v10 offset:17152
	v_pk_fma_f32 v[68:69], v[2:3], v[24:25], v[68:69] op_sel_hi:[1,0,1]
	v_add_f32_dpp v79, v78, v78 quad_perm:[3,2,1,0] row_mask:0xf bank_mask:0xf bound_ctrl:1
	ds_read_b128 v[52:55], v10 offset:25344
	ds_read_b128 v[56:59], v10 offset:33536
	v_pk_fma_f32 v[70:71], v[4:5], v[24:25], v[70:71] op_sel:[0,1,0] op_sel_hi:[1,1,1]
	v_add_f32_dpp v80, v79, v79 row_half_mirror row_mask:0xf bank_mask:0xf bound_ctrl:1
	ds_read_b32 v60, v11 offset:41344
	ds_read_b32 v61, v12 offset:41344
	v_pk_fma_f32 v[72:73], v[6:7], v[26:27], v[72:73] op_sel_hi:[1,0,1]
	v_add_f32_dpp v76, v80, v80 row_mirror row_mask:0xf bank_mask:0xf bound_ctrl:1
	ds_read_b64 v[62:63], v13 offset:45080
	v_pk_fma_f32 v[74:75], v[8:9], v[26:27], v[74:75] op_sel:[0,1,0] op_sel_hi:[1,1,1]
	v_mul_f32_e32 v83, v36, v38
	v_mov_b32_dpp v77, v76 quad_perm:[1,0,3,2] row_mask:0xf bank_mask:0xf bound_ctrl:1
	v_add_f32_dpp v81, v67, v66 quad_perm:[1,0,3,2] row_mask:0xf bank_mask:0xf bound_ctrl:1
	v_pk_fma_f32 v[2:3], v[32:33], v[76:77], v[68:69] op_sel_hi:[0,1,1] neg_lo:[1,0,0] neg_hi:[1,0,0]
	v_pk_fma_f32 v[4:5], v[32:33], v[76:77], v[70:71] op_sel:[1,0,0] op_sel_hi:[1,1,1] neg_lo:[1,0,0] neg_hi:[1,0,0]
	v_pk_fma_f32 v[6:7], v[34:35], v[76:77], v[72:73] op_sel_hi:[0,1,1] neg_lo:[1,0,0] neg_hi:[1,0,0]
	v_pk_fma_f32 v[8:9], v[34:35], v[76:77], v[74:75] op_sel:[1,0,0] op_sel_hi:[1,1,1] neg_lo:[1,0,0] neg_hi:[1,0,0]
	v_fma_f32 v83, -v76, v39, v83
	v_add_f32_dpp v82, v81, v81 quad_perm:[3,2,1,0] row_mask:0xf bank_mask:0xf bound_ctrl:1
	v_fmac_f32_e32 v82, 0x3e800000, v83
	ds_write_b32 v14, v82 offset:1024
	s_waitcnt lgkmcnt(1)
	v_pk_mul_f32 v[64:65], v[2:3], v[40:41] op_sel_hi:[1,0]
	v_pk_mul_f32 v[66:67], v[2:3], v[44:45] op_sel_hi:[1,0]
	v_pk_mul_f32 v[68:69], v[60:61], v[52:53] op_sel_hi:[1,0]
	v_pk_fma_f32 v[64:65], v[4:5], v[40:41], v[64:65] op_sel:[0,1,0] op_sel_hi:[1,1,1]
	v_pk_fma_f32 v[66:67], v[4:5], v[44:45], v[66:67] op_sel:[0,1,0] op_sel_hi:[1,1,1]
	v_pk_mul_f32 v[70:71], v[60:61], v[52:53] op_sel:[0,1] op_sel_hi:[1,1]
	v_pk_fma_f32 v[64:65], v[6:7], v[42:43], v[64:65] op_sel_hi:[1,0,1]
	v_pk_fma_f32 v[66:67], v[6:7], v[46:47], v[66:67] op_sel_hi:[1,0,1]
	v_pk_mul_f32 v[72:73], v[60:61], v[54:55] op_sel_hi:[1,0]
	v_pk_fma_f32 v[64:65], v[8:9], v[42:43], v[64:65] op_sel:[0,1,0] op_sel_hi:[1,1,1]
	v_pk_fma_f32 v[66:67], v[8:9], v[46:47], v[66:67] op_sel:[0,1,0] op_sel_hi:[1,1,1]
	v_pk_mul_f32 v[74:75], v[60:61], v[54:55] op_sel:[0,1] op_sel_hi:[1,1]
	ds_read_b128 v[16:19], v10 offset:1024
	v_add_f32_dpp v78, v65, v64 quad_perm:[1,0,3,2] row_mask:0xf bank_mask:0xf bound_ctrl:1
	ds_read_b128 v[20:23], v10 offset:9216
	ds_read_b128 v[24:27], v10 offset:17408
	v_pk_fma_f32 v[68:69], v[2:3], v[48:49], v[68:69] op_sel_hi:[1,0,1]
	v_add_f32_dpp v79, v78, v78 quad_perm:[3,2,1,0] row_mask:0xf bank_mask:0xf bound_ctrl:1
	ds_read_b128 v[28:31], v10 offset:25600
	ds_read_b128 v[32:35], v10 offset:33792
	v_pk_fma_f32 v[70:71], v[4:5], v[48:49], v[70:71] op_sel:[0,1,0] op_sel_hi:[1,1,1]
	v_add_f32_dpp v80, v79, v79 row_half_mirror row_mask:0xf bank_mask:0xf bound_ctrl:1
	ds_read_b32 v36, v11 offset:41472
	ds_read_b32 v37, v12 offset:41472
	v_pk_fma_f32 v[72:73], v[6:7], v[50:51], v[72:73] op_sel_hi:[1,0,1]
	v_add_f32_dpp v76, v80, v80 row_mirror row_mask:0xf bank_mask:0xf bound_ctrl:1
	ds_read_b64 v[38:39], v13 offset:45088
	v_pk_fma_f32 v[74:75], v[8:9], v[50:51], v[74:75] op_sel:[0,1,0] op_sel_hi:[1,1,1]
	v_mul_f32_e32 v83, v60, v62
	v_mov_b32_dpp v77, v76 quad_perm:[1,0,3,2] row_mask:0xf bank_mask:0xf bound_ctrl:1
	v_add_f32_dpp v81, v67, v66 quad_perm:[1,0,3,2] row_mask:0xf bank_mask:0xf bound_ctrl:1
	v_pk_fma_f32 v[2:3], v[56:57], v[76:77], v[68:69] op_sel_hi:[0,1,1] neg_lo:[1,0,0] neg_hi:[1,0,0]
	v_pk_fma_f32 v[4:5], v[56:57], v[76:77], v[70:71] op_sel:[1,0,0] op_sel_hi:[1,1,1] neg_lo:[1,0,0] neg_hi:[1,0,0]
	v_pk_fma_f32 v[6:7], v[58:59], v[76:77], v[72:73] op_sel_hi:[0,1,1] neg_lo:[1,0,0] neg_hi:[1,0,0]
	v_pk_fma_f32 v[8:9], v[58:59], v[76:77], v[74:75] op_sel:[1,0,0] op_sel_hi:[1,1,1] neg_lo:[1,0,0] neg_hi:[1,0,0]
	v_fma_f32 v83, -v76, v63, v83
	v_add_f32_dpp v82, v81, v81 quad_perm:[3,2,1,0] row_mask:0xf bank_mask:0xf bound_ctrl:1
	v_fmac_f32_e32 v82, 0x3e800000, v83
	ds_write_b32 v14, v82 offset:1536
	s_waitcnt lgkmcnt(1)
; #define LAS __attribute__((address_space(3)))
; template <int CTRL> __device__ __forceinline__ float dppf(float x) { return __builtin_bit_cast(float, __builtin_amdgcn_mov_dpp(__builtin_bit_cast(int, x), CTRL, 0xf, 0xf, true)); }
; __device__ __forceinline__ float sum16(float x) { x = sum8(x); x += dppf<0x140>(x); return x; }
; __device__ __forceinline__ void rwkv_item(LAS unsigned char* lds, int l, const bf16_t* PROJ, const bf16_t* LO, bf16_t* YR, float* BON, int b, int h, int qv) {
;     ...
;             for (int t = 0; t < CH; ++t) {
;                 const int tn = (t + 1) & (CH - 1);
;                 const LAS float* pn = pk + tn * 64;
;                 const f32x4 nkk = *(const LAS f32x4*)(pn), nwr = *(const LAS f32x4*)(pn + 2048), nw = *(const LAS f32x4*)(pn + 4096), nk = *(const LAS f32x4*)(pn + 6144), na = *(const LAS f32x4*)(pn + 8192);
;                 const float nv0 = pv[tn * 32], nv1 = pv[tn * 32 + 4]; const f32x2 nsc = *(const LAS f32x2*)(ps + 2 * tn);
;                 float sa[2], yp[2];
; #pragma unroll
;                 for (int c = 0; c < 2; ++c) { const f32x2 pa = S23[c] * kk4.hi + S01[c] * kk4.lo, pb = S23[c] * wr4.hi + S01[c] * wr4.lo; sa[c] = pa.x + pa.y; yp[c] = pb.x + pb.y; }
; #pragma unroll
;                 for (int c = 0; c < 2; ++c) { sa[c] = sum16(sa[c]); yp[c] += dppf<0xB1>(yp[c]); yp[c] += dppf<0x4E>(yp[c]); }
; #pragma unroll
;                 for (int c = 0; c < 2; ++c) {
;                     S01[c] = S01[c] * w4.lo + (k4.lo * vv[c] - a4.lo * sa[c]);
;                     S23[c] = S23[c] * w4.hi + (k4.hi * vv[c] - a4.hi * sa[c]);
;                     py[(t * 32 + 4 * c) * 4] = yp[c] + 0.25f * (vv[c] * sc.x - sa[c] * sc.y);
;                 }
;                 kk4 = nkk; wr4 = nwr; w4 = nw; k4 = nk; a4 = na; vv[0] = nv0; vv[1] = nv1; sc = nsc;
;             }
	v_pk_mul_f32 v[64:65], v[2:3], v[16:17] op_sel_hi:[1,0]
	v_pk_mul_f32 v[66:67], v[2:3], v[20:21] op_sel_hi:[1,0]
	v_pk_mul_f32 v[68:69], v[36:37], v[28:29] op_sel_hi:[1,0]
	v_pk_fma_f32 v[64:65], v[4:5], v[16:17], v[64:65] op_sel:[0,1,0] op_sel_hi:[1,1,1]
	v_pk_fma_f32 v[66:67], v[4:5], v[20:21], v[66:67] op_sel:[0,1,0] op_sel_hi:[1,1,1]
	v_pk_mul_f32 v[70:71], v[36:37], v[28:29] op_sel:[0,1] op_sel_hi:[1,1]
	v_pk_fma_f32 v[64:65], v[6:7], v[18:19], v[64:65] op_sel_hi:[1,0,1]
	v_pk_fma_f32 v[66:67], v[6:7], v[22:23], v[66:67] op_sel_hi:[1,0,1]
	v_pk_mul_f32 v[72:73], v[36:37], v[30:31] op_sel_hi:[1,0]
	v_pk_fma_f32 v[64:65], v[8:9], v[18:19], v[64:65] op_sel:[0,1,0] op_sel_hi:[1,1,1]
	v_pk_fma_f32 v[66:67], v[8:9], v[22:23], v[66:67] op_sel:[0,1,0] op_sel_hi:[1,1,1]
	v_pk_mul_f32 v[74:75], v[36:37], v[30:31] op_sel:[0,1] op_sel_hi:[1,1]
	ds_read_b128 v[40:43], v10 offset:1280
	v_add_f32_dpp v78, v65, v64 quad_perm:[1,0,3,2] row_mask:0xf bank_mask:0xf bound_ctrl:1
	ds_read_b128 v[44:47], v10 offset:9472
	ds_read_b128 v[48:51], v10 offset:17664
	v_pk_fma_f32 v[68:69], v[2:3], v[24:25], v[68:69] op_sel_hi:[1,0,1]
	v_add_f32_dpp v79, v78, v78 quad_perm:[3,2,1,0] row_mask:0xf bank_mask:0xf bound_ctrl:1
	ds_read_b128 v[52:55], v10 offset:25856
	ds_read_b128 v[56:59], v10 offset:34048
	v_pk_fma_f32 v[70:71], v[4:5], v[24:25], v[70:71] op_sel:[0,1,0] op_sel_hi:[1,1,1]
	v_add_f32_dpp v80, v79, v79 row_half_mirror row_mask:0xf bank_mask:0xf bound_ctrl:1
	ds_read_b32 v60, v11 offset:41600
	ds_read_b32 v61, v12 offset:41600
	v_pk_fma_f32 v[72:73], v[6:7], v[26:27], v[72:73] op_sel_hi:[1,0,1]
	v_add_f32_dpp v76, v80, v80 row_mirror row_mask:0xf bank_mask:0xf bound_ctrl:1
	ds_read_b64 v[62:63], v13 offset:45096
	v_pk_fma_f32 v[74:75], v[8:9], v[26:27], v[74:75] op_sel:[0,1,0] op_sel_hi:[1,1,1]
	v_mul_f32_e32 v83, v36, v38
	v_mov_b32_dpp v77, v76 quad_perm:[1,0,3,2] row_mask:0xf bank_mask:0xf bound_ctrl:1
	v_add_f32_dpp v81, v67, v66 quad_perm:[1,0,3,2] row_mask:0xf bank_mask:0xf bound_ctrl:1
	v_pk_fma_f32 v[2:3], v[32:33], v[76:77], v[68:69] op_sel_hi:[0,1,1] neg_lo:[1,0,0] neg_hi:[1,0,0]
	v_pk_fma_f32 v[4:5], v[32:33], v[76:77], v[70:71] op_sel:[1,0,0] op_sel_hi:[1,1,1] neg_lo:[1,0,0] neg_hi:[1,0,0]
	v_pk_fma_f32 v[6:7], v[34:35], v[76:77], v[72:73] op_sel_hi:[0,1,1] neg_lo:[1,0,0] neg_hi:[1,0,0]
	v_pk_fma_f32 v[8:9], v[34:35], v[76:77], v[74:75] op_sel:[1,0,0] op_sel_hi:[1,1,1] neg_lo:[1,0,0] neg_hi:[1,0,0]
	v_fma_f32 v83, -v76, v39, v83
	v_add_f32_dpp v82, v81, v81 quad_perm:[3,2,1,0] row_mask:0xf bank_mask:0xf bound_ctrl:1
	v_fmac_f32_e32 v82, 0x3e800000, v83
	ds_write_b32 v14, v82 offset:2048
	s_waitcnt lgkmcnt(1)
	v_pk_mul_f32 v[64:65], v[2:3], v[40:41] op_sel_hi:[1,0]
	v_pk_mul_f32 v[66:67], v[2:3], v[44:45] op_sel_hi:[1,0]
	v_pk_mul_f32 v[68:69], v[60:61], v[52:53] op_sel_hi:[1,0]
	v_pk_fma_f32 v[64:65], v[4:5], v[40:41], v[64:65] op_sel:[0,1,0] op_sel_hi:[1,1,1]
	v_pk_fma_f32 v[66:67], v[4:5], v[44:45], v[66:67] op_sel:[0,1,0] op_sel_hi:[1,1,1]
	v_pk_mul_f32 v[70:71], v[60:61], v[52:53] op_sel:[0,1] op_sel_hi:[1,1]
	v_pk_fma_f32 v[64:65], v[6:7], v[42:43], v[64:65] op_sel_hi:[1,0,1]
	v_pk_fma_f32 v[66:67], v[6:7], v[46:47], v[66:67] op_sel_hi:[1,0,1]
	v_pk_mul_f32 v[72:73], v[60:61], v[54:55] op_sel_hi:[1,0]
	v_pk_fma_f32 v[64:65], v[8:9], v[42:43], v[64:65] op_sel:[0,1,0] op_sel_hi:[1,1,1]
	v_pk_fma_f32 v[66:67], v[8:9], v[46:47], v[66:67] op_sel:[0,1,0] op_sel_hi:[1,1,1]
	v_pk_mul_f32 v[74:75], v[60:61], v[54:55] op_sel:[0,1] op_sel_hi:[1,1]
	ds_read_b128 v[16:19], v10 offset:1536
	v_add_f32_dpp v78, v65, v64 quad_perm:[1,0,3,2] row_mask:0xf bank_mask:0xf bound_ctrl:1
	ds_read_b128 v[20:23], v10 offset:9728
	ds_read_b128 v[24:27], v10 offset:17920
	v_pk_fma_f32 v[68:69], v[2:3], v[48:49], v[68:69] op_sel_hi:[1,0,1]
	v_add_f32_dpp v79, v78, v78 quad_perm:[3,2,1,0] row_mask:0xf bank_mask:0xf bound_ctrl:1
	ds_read_b128 v[28:31], v10 offset:26112
	ds_read_b128 v[32:35], v10 offset:34304
	v_pk_fma_f32 v[70:71], v[4:5], v[48:49], v[70:71] op_sel:[0,1,0] op_sel_hi:[1,1,1]
	v_add_f32_dpp v80, v79, v79 row_half_mirror row_mask:0xf bank_mask:0xf bound_ctrl:1
	ds_read_b32 v36, v11 offset:41728
	ds_read_b32 v37, v12 offset:41728
	v_pk_fma_f32 v[72:73], v[6:7], v[50:51], v[72:73] op_sel_hi:[1,0,1]
	v_add_f32_dpp v76, v80, v80 row_mirror row_mask:0xf bank_mask:0xf bound_ctrl:1
	ds_read_b64 v[38:39], v13 offset:45104
	v_pk_fma_f32 v[74:75], v[8:9], v[50:51], v[74:75] op_sel:[0,1,0] op_sel_hi:[1,1,1]
	v_mul_f32_e32 v83, v60, v62
	v_mov_b32_dpp v77, v76 quad_perm:[1,0,3,2] row_mask:0xf bank_mask:0xf bound_ctrl:1
	v_add_f32_dpp v81, v67, v66 quad_perm:[1,0,3,2] row_mask:0xf bank_mask:0xf bound_ctrl:1
	v_pk_fma_f32 v[2:3], v[56:57], v[76:77], v[68:69] op_sel_hi:[0,1,1] neg_lo:[1,0,0] neg_hi:[1,0,0]
	v_pk_fma_f32 v[4:5], v[56:57], v[76:77], v[70:71] op_sel:[1,0,0] op_sel_hi:[1,1,1] neg_lo:[1,0,0] neg_hi:[1,0,0]
	v_pk_fma_f32 v[6:7], v[58:59], v[76:77], v[72:73] op_sel_hi:[0,1,1] neg_lo:[1,0,0] neg_hi:[1,0,0]
	v_pk_fma_f32 v[8:9], v[58:59], v[76:77], v[74:75] op_sel:[1,0,0] op_sel_hi:[1,1,1] neg_lo:[1,0,0] neg_hi:[1,0,0]
	v_fma_f32 v83, -v76, v63, v83
	v_add_f32_dpp v82, v81, v81 quad_perm:[3,2,1,0] row_mask:0xf bank_mask:0xf bound_ctrl:1
	v_fmac_f32_e32 v82, 0x3e800000, v83
	ds_write_b32 v14, v82 offset:2560
	s_waitcnt lgkmcnt(1)
; #define LAS __attribute__((address_space(3)))
; template <int CTRL> __device__ __forceinline__ float dppf(float x) { return __builtin_bit_cast(float, __builtin_amdgcn_mov_dpp(__builtin_bit_cast(int, x), CTRL, 0xf, 0xf, true)); }
; __device__ __forceinline__ float sum16(float x) { x = sum8(x); x += dppf<0x140>(x); return x; }
; __device__ __forceinline__ void rwkv_item(LAS unsigned char* lds, int l, const bf16_t* PROJ, const bf16_t* LO, bf16_t* YR, float* BON, int b, int h, int qv) {
;     ...
;             for (int t = 0; t < CH; ++t) {
;                 const int tn = (t + 1) & (CH - 1);
;                 const LAS float* pn = pk + tn * 64;
;                 const f32x4 nkk = *(const LAS f32x4*)(pn), nwr = *(const LAS f32x4*)(pn + 2048), nw = *(const LAS f32x4*)(pn + 4096), nk = *(const LAS f32x4*)(pn + 6144), na = *(const LAS f32x4*)(pn + 8192);
;                 const float nv0 = pv[tn * 32], nv1 = pv[tn * 32 + 4]; const f32x2 nsc = *(const LAS f32x2*)(ps + 2 * tn);
;                 float sa[2], yp[2];
; #pragma unroll
;                 for (int c = 0; c < 2; ++c) { const f32x2 pa = S23[c] * kk4.hi + S01[c] * kk4.lo, pb = S23[c] * wr4.hi + S01[c] * wr4.lo; sa[c] = pa.x + pa.y; yp[c] = pb.x + pb.y; }
; #pragma unroll
;                 for (int c = 0; c < 2; ++c) { sa[c] = sum16(sa[c]); yp[c] += dppf<0xB1>(yp[c]); yp[c] += dppf<0x4E>(yp[c]); }
; #pragma unroll
;                 for (int c = 0; c < 2; ++c) {
;                     S01[c] = S01[c] * w4.lo + (k4.lo * vv[c] - a4.lo * sa[c]);
;                     S23[c] = S23[c] * w4.hi + (k4.hi * vv[c] - a4.hi * sa[c]);
;                     py[(t * 32 + 4 * c) * 4] = yp[c] + 0.25f * (vv[c] * sc.x - sa[c] * sc.y);
;                 }
;                 kk4 = nkk; wr4 = nwr; w4 = nw; k4 = nk; a4 = na; vv[0] = nv0; vv[1] = nv1; sc = nsc;
;             }
	v_pk_mul_f32 v[64:65], v[2:3], v[16:17] op_sel_hi:[1,0]
	v_pk_mul_f32 v[66:67], v[2:3], v[20:21] op_sel_hi:[1,0]
	v_pk_mul_f32 v[68:69], v[36:37], v[28:29] op_sel_hi:[1,0]
	v_pk_fma_f32 v[64:65], v[4:5], v[16:17], v[64:65] op_sel:[0,1,0] op_sel_hi:[1,1,1]
	v_pk_fma_f32 v[66:67], v[4:5], v[20:21], v[66:67] op_sel:[0,1,0] op_sel_hi:[1,1,1]
	v_pk_mul_f32 v[70:71], v[36:37], v[28:29] op_sel:[0,1] op_sel_hi:[1,1]
	v_pk_fma_f32 v[64:65], v[6:7], v[18:19], v[64:65] op_sel_hi:[1,0,1]
	v_pk_fma_f32 v[66:67], v[6:7], v[22:23], v[66:67] op_sel_hi:[1,0,1]
	v_pk_mul_f32 v[72:73], v[36:37], v[30:31] op_sel_hi:[1,0]
	v_pk_fma_f32 v[64:65], v[8:9], v[18:19], v[64:65] op_sel:[0,1,0] op_sel_hi:[1,1,1]
	v_pk_fma_f32 v[66:67], v[8:9], v[22:23], v[66:67] op_sel:[0,1,0] op_sel_hi:[1,1,1]
	v_pk_mul_f32 v[74:75], v[36:37], v[30:31] op_sel:[0,1] op_sel_hi:[1,1]
	ds_read_b128 v[40:43], v10 offset:1792
	v_add_f32_dpp v78, v65, v64 quad_perm:[1,0,3,2] row_mask:0xf bank_mask:0xf bound_ctrl:1
	ds_read_b128 v[44:47], v10 offset:9984
	ds_read_b128 v[48:51], v10 offset:18176
	v_pk_fma_f32 v[68:69], v[2:3], v[24:25], v[68:69] op_sel_hi:[1,0,1]
	v_add_f32_dpp v79, v78, v78 quad_perm:[3,2,1,0] row_mask:0xf bank_mask:0xf bound_ctrl:1
	ds_read_b128 v[52:55], v10 offset:26368
	ds_read_b128 v[56:59], v10 offset:34560
	v_pk_fma_f32 v[70:71], v[4:5], v[24:25], v[70:71] op_sel:[0,1,0] op_sel_hi:[1,1,1]
	v_add_f32_dpp v80, v79, v79 row_half_mirror row_mask:0xf bank_mask:0xf bound_ctrl:1
	ds_read_b32 v60, v11 offset:41856
	ds_read_b32 v61, v12 offset:41856
	v_pk_fma_f32 v[72:73], v[6:7], v[26:27], v[72:73] op_sel_hi:[1,0,1]
	v_add_f32_dpp v76, v80, v80 row_mirror row_mask:0xf bank_mask:0xf bound_ctrl:1
	ds_read_b64 v[62:63], v13 offset:45112
	v_pk_fma_f32 v[74:75], v[8:9], v[26:27], v[74:75] op_sel:[0,1,0] op_sel_hi:[1,1,1]
	v_mul_f32_e32 v83, v36, v38
	v_mov_b32_dpp v77, v76 quad_perm:[1,0,3,2] row_mask:0xf bank_mask:0xf bound_ctrl:1
	v_add_f32_dpp v81, v67, v66 quad_perm:[1,0,3,2] row_mask:0xf bank_mask:0xf bound_ctrl:1
	v_pk_fma_f32 v[2:3], v[32:33], v[76:77], v[68:69] op_sel_hi:[0,1,1] neg_lo:[1,0,0] neg_hi:[1,0,0]
	v_pk_fma_f32 v[4:5], v[32:33], v[76:77], v[70:71] op_sel:[1,0,0] op_sel_hi:[1,1,1] neg_lo:[1,0,0] neg_hi:[1,0,0]
	v_pk_fma_f32 v[6:7], v[34:35], v[76:77], v[72:73] op_sel_hi:[0,1,1] neg_lo:[1,0,0] neg_hi:[1,0,0]
	v_pk_fma_f32 v[8:9], v[34:35], v[76:77], v[74:75] op_sel:[1,0,0] op_sel_hi:[1,1,1] neg_lo:[1,0,0] neg_hi:[1,0,0]
	v_fma_f32 v83, -v76, v39, v83
	v_add_f32_dpp v82, v81, v81 quad_perm:[3,2,1,0] row_mask:0xf bank_mask:0xf bound_ctrl:1
	v_fmac_f32_e32 v82, 0x3e800000, v83
	ds_write_b32 v14, v82 offset:3072
	s_waitcnt lgkmcnt(1)
	v_pk_mul_f32 v[64:65], v[2:3], v[40:41] op_sel_hi:[1,0]
	v_pk_mul_f32 v[66:67], v[2:3], v[44:45] op_sel_hi:[1,0]
	v_pk_mul_f32 v[68:69], v[60:61], v[52:53] op_sel_hi:[1,0]
	v_pk_fma_f32 v[64:65], v[4:5], v[40:41], v[64:65] op_sel:[0,1,0] op_sel_hi:[1,1,1]
	v_pk_fma_f32 v[66:67], v[4:5], v[44:45], v[66:67] op_sel:[0,1,0] op_sel_hi:[1,1,1]
	v_pk_mul_f32 v[70:71], v[60:61], v[52:53] op_sel:[0,1] op_sel_hi:[1,1]
	v_pk_fma_f32 v[64:65], v[6:7], v[42:43], v[64:65] op_sel_hi:[1,0,1]
	v_pk_fma_f32 v[66:67], v[6:7], v[46:47], v[66:67] op_sel_hi:[1,0,1]
	v_pk_mul_f32 v[72:73], v[60:61], v[54:55] op_sel_hi:[1,0]
	v_pk_fma_f32 v[64:65], v[8:9], v[42:43], v[64:65] op_sel:[0,1,0] op_sel_hi:[1,1,1]
	v_pk_fma_f32 v[66:67], v[8:9], v[46:47], v[66:67] op_sel:[0,1,0] op_sel_hi:[1,1,1]
	v_pk_mul_f32 v[74:75], v[60:61], v[54:55] op_sel:[0,1] op_sel_hi:[1,1]
	ds_read_b128 v[16:19], v10 offset:2048
	v_add_f32_dpp v78, v65, v64 quad_perm:[1,0,3,2] row_mask:0xf bank_mask:0xf bound_ctrl:1
	ds_read_b128 v[20:23], v10 offset:10240
	ds_read_b128 v[24:27], v10 offset:18432
	v_pk_fma_f32 v[68:69], v[2:3], v[48:49], v[68:69] op_sel_hi:[1,0,1]
	v_add_f32_dpp v79, v78, v78 quad_perm:[3,2,1,0] row_mask:0xf bank_mask:0xf bound_ctrl:1
	ds_read_b128 v[28:31], v10 offset:26624
	ds_read_b128 v[32:35], v10 offset:34816
	v_pk_fma_f32 v[70:71], v[4:5], v[48:49], v[70:71] op_sel:[0,1,0] op_sel_hi:[1,1,1]
	v_add_f32_dpp v80, v79, v79 row_half_mirror row_mask:0xf bank_mask:0xf bound_ctrl:1
	ds_read_b32 v36, v11 offset:41984
	ds_read_b32 v37, v12 offset:41984
	v_pk_fma_f32 v[72:73], v[6:7], v[50:51], v[72:73] op_sel_hi:[1,0,1]
	v_add_f32_dpp v76, v80, v80 row_mirror row_mask:0xf bank_mask:0xf bound_ctrl:1
	ds_read_b64 v[38:39], v13 offset:45120
	v_pk_fma_f32 v[74:75], v[8:9], v[50:51], v[74:75] op_sel:[0,1,0] op_sel_hi:[1,1,1]
	v_mul_f32_e32 v83, v60, v62
	v_mov_b32_dpp v77, v76 quad_perm:[1,0,3,2] row_mask:0xf bank_mask:0xf bound_ctrl:1
	v_add_f32_dpp v81, v67, v66 quad_perm:[1,0,3,2] row_mask:0xf bank_mask:0xf bound_ctrl:1
	v_pk_fma_f32 v[2:3], v[56:57], v[76:77], v[68:69] op_sel_hi:[0,1,1] neg_lo:[1,0,0] neg_hi:[1,0,0]
	v_pk_fma_f32 v[4:5], v[56:57], v[76:77], v[70:71] op_sel:[1,0,0] op_sel_hi:[1,1,1] neg_lo:[1,0,0] neg_hi:[1,0,0]
	v_pk_fma_f32 v[6:7], v[58:59], v[76:77], v[72:73] op_sel_hi:[0,1,1] neg_lo:[1,0,0] neg_hi:[1,0,0]
	v_pk_fma_f32 v[8:9], v[58:59], v[76:77], v[74:75] op_sel:[1,0,0] op_sel_hi:[1,1,1] neg_lo:[1,0,0] neg_hi:[1,0,0]
	v_fma_f32 v83, -v76, v63, v83
	v_add_f32_dpp v82, v81, v81 quad_perm:[3,2,1,0] row_mask:0xf bank_mask:0xf bound_ctrl:1
	v_fmac_f32_e32 v82, 0x3e800000, v83
	ds_write_b32 v14, v82 offset:3584
	s_waitcnt lgkmcnt(1)
; #define LAS __attribute__((address_space(3)))
; template <int CTRL> __device__ __forceinline__ float dppf(float x) { return __builtin_bit_cast(float, __builtin_amdgcn_mov_dpp(__builtin_bit_cast(int, x), CTRL, 0xf, 0xf, true)); }
; __device__ __forceinline__ float sum16(float x) { x = sum8(x); x += dppf<0x140>(x); return x; }
; __device__ __forceinline__ void rwkv_item(LAS unsigned char* lds, int l, const bf16_t* PROJ, const bf16_t* LO, bf16_t* YR, float* BON, int b, int h, int qv) {
;     ...
;             for (int t = 0; t < CH; ++t) {
;                 const int tn = (t + 1) & (CH - 1);
;                 const LAS float* pn = pk + tn * 64;
;                 const f32x4 nkk = *(const LAS f32x4*)(pn), nwr = *(const LAS f32x4*)(pn + 2048), nw = *(const LAS f32x4*)(pn + 4096), nk = *(const LAS f32x4*)(pn + 6144), na = *(const LAS f32x4*)(pn + 8192);
;                 const float nv0 = pv[tn * 32], nv1 = pv[tn * 32 + 4]; const f32x2 nsc = *(const LAS f32x2*)(ps + 2 * tn);
;                 float sa[2], yp[2];
; #pragma unroll
;                 for (int c = 0; c < 2; ++c) { const f32x2 pa = S23[c] * kk4.hi + S01[c] * kk4.lo, pb = S23[c] * wr4.hi + S01[c] * wr4.lo; sa[c] = pa.x + pa.y; yp[c] = pb.x + pb.y; }
; #pragma unroll
;                 for (int c = 0; c < 2; ++c) { sa[c] = sum16(sa[c]); yp[c] += dppf<0xB1>(yp[c]); yp[c] += dppf<0x4E>(yp[c]); }
; #pragma unroll
;                 for (int c = 0; c < 2; ++c) {
;                     S01[c] = S01[c] * w4.lo + (k4.lo * vv[c] - a4.lo * sa[c]);
;                     S23[c] = S23[c] * w4.hi + (k4.hi * vv[c] - a4.hi * sa[c]);
;                     py[(t * 32 + 4 * c) * 4] = yp[c] + 0.25f * (vv[c] * sc.x - sa[c] * sc.y);
;                 }
;                 kk4 = nkk; wr4 = nwr; w4 = nw; k4 = nk; a4 = na; vv[0] = nv0; vv[1] = nv1; sc = nsc;
;             }
	v_pk_mul_f32 v[64:65], v[2:3], v[16:17] op_sel_hi:[1,0]
	v_pk_mul_f32 v[66:67], v[2:3], v[20:21] op_sel_hi:[1,0]
	v_pk_mul_f32 v[68:69], v[36:37], v[28:29] op_sel_hi:[1,0]
	v_pk_fma_f32 v[64:65], v[4:5], v[16:17], v[64:65] op_sel:[0,1,0] op_sel_hi:[1,1,1]
	v_pk_fma_f32 v[66:67], v[4:5], v[20:21], v[66:67] op_sel:[0,1,0] op_sel_hi:[1,1,1]
	v_pk_mul_f32 v[70:71], v[36:37], v[28:29] op_sel:[0,1] op_sel_hi:[1,1]
	v_pk_fma_f32 v[64:65], v[6:7], v[18:19], v[64:65] op_sel_hi:[1,0,1]
	v_pk_fma_f32 v[66:67], v[6:7], v[22:23], v[66:67] op_sel_hi:[1,0,1]
	v_pk_mul_f32 v[72:73], v[36:37], v[30:31] op_sel_hi:[1,0]
	v_pk_fma_f32 v[64:65], v[8:9], v[18:19], v[64:65] op_sel:[0,1,0] op_sel_hi:[1,1,1]
	v_pk_fma_f32 v[66:67], v[8:9], v[22:23], v[66:67] op_sel:[0,1,0] op_sel_hi:[1,1,1]
	v_pk_mul_f32 v[74:75], v[36:37], v[30:31] op_sel:[0,1] op_sel_hi:[1,1]
	ds_read_b128 v[40:43], v10 offset:2304
	v_add_f32_dpp v78, v65, v64 quad_perm:[1,0,3,2] row_mask:0xf bank_mask:0xf bound_ctrl:1
	ds_read_b128 v[44:47], v10 offset:10496
	ds_read_b128 v[48:51], v10 offset:18688
	v_pk_fma_f32 v[68:69], v[2:3], v[24:25], v[68:69] op_sel_hi:[1,0,1]
	v_add_f32_dpp v79, v78, v78 quad_perm:[3,2,1,0] row_mask:0xf bank_mask:0xf bound_ctrl:1
	ds_read_b128 v[52:55], v10 offset:26880
	ds_read_b128 v[56:59], v10 offset:35072
	v_pk_fma_f32 v[70:71], v[4:5], v[24:25], v[70:71] op_sel:[0,1,0] op_sel_hi:[1,1,1]
	v_add_f32_dpp v80, v79, v79 row_half_mirror row_mask:0xf bank_mask:0xf bound_ctrl:1
	ds_read_b32 v60, v11 offset:42112
	ds_read_b32 v61, v12 offset:42112
	v_pk_fma_f32 v[72:73], v[6:7], v[26:27], v[72:73] op_sel_hi:[1,0,1]
	v_add_f32_dpp v76, v80, v80 row_mirror row_mask:0xf bank_mask:0xf bound_ctrl:1
	ds_read_b64 v[62:63], v13 offset:45128
	v_pk_fma_f32 v[74:75], v[8:9], v[26:27], v[74:75] op_sel:[0,1,0] op_sel_hi:[1,1,1]
	v_mul_f32_e32 v83, v36, v38
	v_mov_b32_dpp v77, v76 quad_perm:[1,0,3,2] row_mask:0xf bank_mask:0xf bound_ctrl:1
	v_add_f32_dpp v81, v67, v66 quad_perm:[1,0,3,2] row_mask:0xf bank_mask:0xf bound_ctrl:1
	v_pk_fma_f32 v[2:3], v[32:33], v[76:77], v[68:69] op_sel_hi:[0,1,1] neg_lo:[1,0,0] neg_hi:[1,0,0]
	v_pk_fma_f32 v[4:5], v[32:33], v[76:77], v[70:71] op_sel:[1,0,0] op_sel_hi:[1,1,1] neg_lo:[1,0,0] neg_hi:[1,0,0]
	v_pk_fma_f32 v[6:7], v[34:35], v[76:77], v[72:73] op_sel_hi:[0,1,1] neg_lo:[1,0,0] neg_hi:[1,0,0]
	v_pk_fma_f32 v[8:9], v[34:35], v[76:77], v[74:75] op_sel:[1,0,0] op_sel_hi:[1,1,1] neg_lo:[1,0,0] neg_hi:[1,0,0]
	v_fma_f32 v83, -v76, v39, v83
	v_add_f32_dpp v82, v81, v81 quad_perm:[3,2,1,0] row_mask:0xf bank_mask:0xf bound_ctrl:1
	v_fmac_f32_e32 v82, 0x3e800000, v83
	ds_write_b32 v14, v82 offset:4096
	s_waitcnt lgkmcnt(1)
	v_pk_mul_f32 v[64:65], v[2:3], v[40:41] op_sel_hi:[1,0]
	v_pk_mul_f32 v[66:67], v[2:3], v[44:45] op_sel_hi:[1,0]
	v_pk_mul_f32 v[68:69], v[60:61], v[52:53] op_sel_hi:[1,0]
	v_pk_fma_f32 v[64:65], v[4:5], v[40:41], v[64:65] op_sel:[0,1,0] op_sel_hi:[1,1,1]
	v_pk_fma_f32 v[66:67], v[4:5], v[44:45], v[66:67] op_sel:[0,1,0] op_sel_hi:[1,1,1]
	v_pk_mul_f32 v[70:71], v[60:61], v[52:53] op_sel:[0,1] op_sel_hi:[1,1]
	v_pk_fma_f32 v[64:65], v[6:7], v[42:43], v[64:65] op_sel_hi:[1,0,1]
	v_pk_fma_f32 v[66:67], v[6:7], v[46:47], v[66:67] op_sel_hi:[1,0,1]
	v_pk_mul_f32 v[72:73], v[60:61], v[54:55] op_sel_hi:[1,0]
	v_pk_fma_f32 v[64:65], v[8:9], v[42:43], v[64:65] op_sel:[0,1,0] op_sel_hi:[1,1,1]
	v_pk_fma_f32 v[66:67], v[8:9], v[46:47], v[66:67] op_sel:[0,1,0] op_sel_hi:[1,1,1]
	v_pk_mul_f32 v[74:75], v[60:61], v[54:55] op_sel:[0,1] op_sel_hi:[1,1]
	ds_read_b128 v[16:19], v10 offset:2560
	v_add_f32_dpp v78, v65, v64 quad_perm:[1,0,3,2] row_mask:0xf bank_mask:0xf bound_ctrl:1
	ds_read_b128 v[20:23], v10 offset:10752
	ds_read_b128 v[24:27], v10 offset:18944
	v_pk_fma_f32 v[68:69], v[2:3], v[48:49], v[68:69] op_sel_hi:[1,0,1]
	v_add_f32_dpp v79, v78, v78 quad_perm:[3,2,1,0] row_mask:0xf bank_mask:0xf bound_ctrl:1
	ds_read_b128 v[28:31], v10 offset:27136
	ds_read_b128 v[32:35], v10 offset:35328
	v_pk_fma_f32 v[70:71], v[4:5], v[48:49], v[70:71] op_sel:[0,1,0] op_sel_hi:[1,1,1]
	v_add_f32_dpp v80, v79, v79 row_half_mirror row_mask:0xf bank_mask:0xf bound_ctrl:1
	ds_read_b32 v36, v11 offset:42240
	ds_read_b32 v37, v12 offset:42240
	v_pk_fma_f32 v[72:73], v[6:7], v[50:51], v[72:73] op_sel_hi:[1,0,1]
	v_add_f32_dpp v76, v80, v80 row_mirror row_mask:0xf bank_mask:0xf bound_ctrl:1
	ds_read_b64 v[38:39], v13 offset:45136
	v_pk_fma_f32 v[74:75], v[8:9], v[50:51], v[74:75] op_sel:[0,1,0] op_sel_hi:[1,1,1]
	v_mul_f32_e32 v83, v60, v62
	v_mov_b32_dpp v77, v76 quad_perm:[1,0,3,2] row_mask:0xf bank_mask:0xf bound_ctrl:1
	v_add_f32_dpp v81, v67, v66 quad_perm:[1,0,3,2] row_mask:0xf bank_mask:0xf bound_ctrl:1
	v_pk_fma_f32 v[2:3], v[56:57], v[76:77], v[68:69] op_sel_hi:[0,1,1] neg_lo:[1,0,0] neg_hi:[1,0,0]
	v_pk_fma_f32 v[4:5], v[56:57], v[76:77], v[70:71] op_sel:[1,0,0] op_sel_hi:[1,1,1] neg_lo:[1,0,0] neg_hi:[1,0,0]
	v_pk_fma_f32 v[6:7], v[58:59], v[76:77], v[72:73] op_sel_hi:[0,1,1] neg_lo:[1,0,0] neg_hi:[1,0,0]
	v_pk_fma_f32 v[8:9], v[58:59], v[76:77], v[74:75] op_sel:[1,0,0] op_sel_hi:[1,1,1] neg_lo:[1,0,0] neg_hi:[1,0,0]
	v_fma_f32 v83, -v76, v63, v83
	v_add_f32_dpp v82, v81, v81 quad_perm:[3,2,1,0] row_mask:0xf bank_mask:0xf bound_ctrl:1
	v_fmac_f32_e32 v82, 0x3e800000, v83
	ds_write_b32 v14, v82 offset:4608
	s_waitcnt lgkmcnt(1)
; #define LAS __attribute__((address_space(3)))
; template <int CTRL> __device__ __forceinline__ float dppf(float x) { return __builtin_bit_cast(float, __builtin_amdgcn_mov_dpp(__builtin_bit_cast(int, x), CTRL, 0xf, 0xf, true)); }
; __device__ __forceinline__ float sum16(float x) { x = sum8(x); x += dppf<0x140>(x); return x; }
; __device__ __forceinline__ void rwkv_item(LAS unsigned char* lds, int l, const bf16_t* PROJ, const bf16_t* LO, bf16_t* YR, float* BON, int b, int h, int qv) {
;     ...
;             for (int t = 0; t < CH; ++t) {
;                 const int tn = (t + 1) & (CH - 1);
;                 const LAS float* pn = pk + tn * 64;
;                 const f32x4 nkk = *(const LAS f32x4*)(pn), nwr = *(const LAS f32x4*)(pn + 2048), nw = *(const LAS f32x4*)(pn + 4096), nk = *(const LAS f32x4*)(pn + 6144), na = *(const LAS f32x4*)(pn + 8192);
;                 const float nv0 = pv[tn * 32], nv1 = pv[tn * 32 + 4]; const f32x2 nsc = *(const LAS f32x2*)(ps + 2 * tn);
;                 float sa[2], yp[2];
; #pragma unroll
;                 for (int c = 0; c < 2; ++c) { const f32x2 pa = S23[c] * kk4.hi + S01[c] * kk4.lo, pb = S23[c] * wr4.hi + S01[c] * wr4.lo; sa[c] = pa.x + pa.y; yp[c] = pb.x + pb.y; }
; #pragma unroll
;                 for (int c = 0; c < 2; ++c) { sa[c] = sum16(sa[c]); yp[c] += dppf<0xB1>(yp[c]); yp[c] += dppf<0x4E>(yp[c]); }
; #pragma unroll
;                 for (int c = 0; c < 2; ++c) {
;                     S01[c] = S01[c] * w4.lo + (k4.lo * vv[c] - a4.lo * sa[c]);
;                     S23[c] = S23[c] * w4.hi + (k4.hi * vv[c] - a4.hi * sa[c]);
;                     py[(t * 32 + 4 * c) * 4] = yp[c] + 0.25f * (vv[c] * sc.x - sa[c] * sc.y);
;                 }
;                 kk4 = nkk; wr4 = nwr; w4 = nw; k4 = nk; a4 = na; vv[0] = nv0; vv[1] = nv1; sc = nsc;
;             }
	v_pk_mul_f32 v[64:65], v[2:3], v[16:17] op_sel_hi:[1,0]
	v_pk_mul_f32 v[66:67], v[2:3], v[20:21] op_sel_hi:[1,0]
	v_pk_mul_f32 v[68:69], v[36:37], v[28:29] op_sel_hi:[1,0]
	v_pk_fma_f32 v[64:65], v[4:5], v[16:17], v[64:65] op_sel:[0,1,0] op_sel_hi:[1,1,1]
	v_pk_fma_f32 v[66:67], v[4:5], v[20:21], v[66:67] op_sel:[0,1,0] op_sel_hi:[1,1,1]
	v_pk_mul_f32 v[70:71], v[36:37], v[28:29] op_sel:[0,1] op_sel_hi:[1,1]
	v_pk_fma_f32 v[64:65], v[6:7], v[18:19], v[64:65] op_sel_hi:[1,0,1]
	v_pk_fma_f32 v[66:67], v[6:7], v[22:23], v[66:67] op_sel_hi:[1,0,1]
	v_pk_mul_f32 v[72:73], v[36:37], v[30:31] op_sel_hi:[1,0]
	v_pk_fma_f32 v[64:65], v[8:9], v[18:19], v[64:65] op_sel:[0,1,0] op_sel_hi:[1,1,1]
	v_pk_fma_f32 v[66:67], v[8:9], v[22:23], v[66:67] op_sel:[0,1,0] op_sel_hi:[1,1,1]
	v_pk_mul_f32 v[74:75], v[36:37], v[30:31] op_sel:[0,1] op_sel_hi:[1,1]
	ds_read_b128 v[40:43], v10 offset:2816
	v_add_f32_dpp v78, v65, v64 quad_perm:[1,0,3,2] row_mask:0xf bank_mask:0xf bound_ctrl:1
	ds_read_b128 v[44:47], v10 offset:11008
	ds_read_b128 v[48:51], v10 offset:19200
	v_pk_fma_f32 v[68:69], v[2:3], v[24:25], v[68:69] op_sel_hi:[1,0,1]
	v_add_f32_dpp v79, v78, v78 quad_perm:[3,2,1,0] row_mask:0xf bank_mask:0xf bound_ctrl:1
	ds_read_b128 v[52:55], v10 offset:27392
	ds_read_b128 v[56:59], v10 offset:35584
	v_pk_fma_f32 v[70:71], v[4:5], v[24:25], v[70:71] op_sel:[0,1,0] op_sel_hi:[1,1,1]
	v_add_f32_dpp v80, v79, v79 row_half_mirror row_mask:0xf bank_mask:0xf bound_ctrl:1
	ds_read_b32 v60, v11 offset:42368
	ds_read_b32 v61, v12 offset:42368
	v_pk_fma_f32 v[72:73], v[6:7], v[26:27], v[72:73] op_sel_hi:[1,0,1]
	v_add_f32_dpp v76, v80, v80 row_mirror row_mask:0xf bank_mask:0xf bound_ctrl:1
	ds_read_b64 v[62:63], v13 offset:45144
	v_pk_fma_f32 v[74:75], v[8:9], v[26:27], v[74:75] op_sel:[0,1,0] op_sel_hi:[1,1,1]
	v_mul_f32_e32 v83, v36, v38
	v_mov_b32_dpp v77, v76 quad_perm:[1,0,3,2] row_mask:0xf bank_mask:0xf bound_ctrl:1
	v_add_f32_dpp v81, v67, v66 quad_perm:[1,0,3,2] row_mask:0xf bank_mask:0xf bound_ctrl:1
	v_pk_fma_f32 v[2:3], v[32:33], v[76:77], v[68:69] op_sel_hi:[0,1,1] neg_lo:[1,0,0] neg_hi:[1,0,0]
	v_pk_fma_f32 v[4:5], v[32:33], v[76:77], v[70:71] op_sel:[1,0,0] op_sel_hi:[1,1,1] neg_lo:[1,0,0] neg_hi:[1,0,0]
	v_pk_fma_f32 v[6:7], v[34:35], v[76:77], v[72:73] op_sel_hi:[0,1,1] neg_lo:[1,0,0] neg_hi:[1,0,0]
	v_pk_fma_f32 v[8:9], v[34:35], v[76:77], v[74:75] op_sel:[1,0,0] op_sel_hi:[1,1,1] neg_lo:[1,0,0] neg_hi:[1,0,0]
	v_fma_f32 v83, -v76, v39, v83
	v_add_f32_dpp v82, v81, v81 quad_perm:[3,2,1,0] row_mask:0xf bank_mask:0xf bound_ctrl:1
	v_fmac_f32_e32 v82, 0x3e800000, v83
	ds_write_b32 v14, v82 offset:5120
	s_waitcnt lgkmcnt(1)
	v_pk_mul_f32 v[64:65], v[2:3], v[40:41] op_sel_hi:[1,0]
	v_pk_mul_f32 v[66:67], v[2:3], v[44:45] op_sel_hi:[1,0]
	v_pk_mul_f32 v[68:69], v[60:61], v[52:53] op_sel_hi:[1,0]
	v_pk_fma_f32 v[64:65], v[4:5], v[40:41], v[64:65] op_sel:[0,1,0] op_sel_hi:[1,1,1]
	v_pk_fma_f32 v[66:67], v[4:5], v[44:45], v[66:67] op_sel:[0,1,0] op_sel_hi:[1,1,1]
	v_pk_mul_f32 v[70:71], v[60:61], v[52:53] op_sel:[0,1] op_sel_hi:[1,1]
	v_pk_fma_f32 v[64:65], v[6:7], v[42:43], v[64:65] op_sel_hi:[1,0,1]
	v_pk_fma_f32 v[66:67], v[6:7], v[46:47], v[66:67] op_sel_hi:[1,0,1]
	v_pk_mul_f32 v[72:73], v[60:61], v[54:55] op_sel_hi:[1,0]
	v_pk_fma_f32 v[64:65], v[8:9], v[42:43], v[64:65] op_sel:[0,1,0] op_sel_hi:[1,1,1]
	v_pk_fma_f32 v[66:67], v[8:9], v[46:47], v[66:67] op_sel:[0,1,0] op_sel_hi:[1,1,1]
	v_pk_mul_f32 v[74:75], v[60:61], v[54:55] op_sel:[0,1] op_sel_hi:[1,1]
	ds_read_b128 v[16:19], v10 offset:3072
	v_add_f32_dpp v78, v65, v64 quad_perm:[1,0,3,2] row_mask:0xf bank_mask:0xf bound_ctrl:1
	ds_read_b128 v[20:23], v10 offset:11264
	ds_read_b128 v[24:27], v10 offset:19456
	v_pk_fma_f32 v[68:69], v[2:3], v[48:49], v[68:69] op_sel_hi:[1,0,1]
	v_add_f32_dpp v79, v78, v78 quad_perm:[3,2,1,0] row_mask:0xf bank_mask:0xf bound_ctrl:1
	ds_read_b128 v[28:31], v10 offset:27648
	ds_read_b128 v[32:35], v10 offset:35840
	v_pk_fma_f32 v[70:71], v[4:5], v[48:49], v[70:71] op_sel:[0,1,0] op_sel_hi:[1,1,1]
	v_add_f32_dpp v80, v79, v79 row_half_mirror row_mask:0xf bank_mask:0xf bound_ctrl:1
	ds_read_b32 v36, v11 offset:42496
	ds_read_b32 v37, v12 offset:42496
	v_pk_fma_f32 v[72:73], v[6:7], v[50:51], v[72:73] op_sel_hi:[1,0,1]
	v_add_f32_dpp v76, v80, v80 row_mirror row_mask:0xf bank_mask:0xf bound_ctrl:1
	ds_read_b64 v[38:39], v13 offset:45152
	v_pk_fma_f32 v[74:75], v[8:9], v[50:51], v[74:75] op_sel:[0,1,0] op_sel_hi:[1,1,1]
	v_mul_f32_e32 v83, v60, v62
	v_mov_b32_dpp v77, v76 quad_perm:[1,0,3,2] row_mask:0xf bank_mask:0xf bound_ctrl:1
	v_add_f32_dpp v81, v67, v66 quad_perm:[1,0,3,2] row_mask:0xf bank_mask:0xf bound_ctrl:1
	v_pk_fma_f32 v[2:3], v[56:57], v[76:77], v[68:69] op_sel_hi:[0,1,1] neg_lo:[1,0,0] neg_hi:[1,0,0]
	v_pk_fma_f32 v[4:5], v[56:57], v[76:77], v[70:71] op_sel:[1,0,0] op_sel_hi:[1,1,1] neg_lo:[1,0,0] neg_hi:[1,0,0]
	v_pk_fma_f32 v[6:7], v[58:59], v[76:77], v[72:73] op_sel_hi:[0,1,1] neg_lo:[1,0,0] neg_hi:[1,0,0]
	v_pk_fma_f32 v[8:9], v[58:59], v[76:77], v[74:75] op_sel:[1,0,0] op_sel_hi:[1,1,1] neg_lo:[1,0,0] neg_hi:[1,0,0]
	v_fma_f32 v83, -v76, v63, v83
	v_add_f32_dpp v82, v81, v81 quad_perm:[3,2,1,0] row_mask:0xf bank_mask:0xf bound_ctrl:1
	v_fmac_f32_e32 v82, 0x3e800000, v83
	ds_write_b32 v14, v82 offset:5632
	s_waitcnt lgkmcnt(1)
; #define LAS __attribute__((address_space(3)))
; template <int CTRL> __device__ __forceinline__ float dppf(float x) { return __builtin_bit_cast(float, __builtin_amdgcn_mov_dpp(__builtin_bit_cast(int, x), CTRL, 0xf, 0xf, true)); }
; __device__ __forceinline__ float sum16(float x) { x = sum8(x); x += dppf<0x140>(x); return x; }
; __device__ __forceinline__ void rwkv_item(LAS unsigned char* lds, int l, const bf16_t* PROJ, const bf16_t* LO, bf16_t* YR, float* BON, int b, int h, int qv) {
;     ...
;             for (int t = 0; t < CH; ++t) {
;                 const int tn = (t + 1) & (CH - 1);
;                 const LAS float* pn = pk + tn * 64;
;                 const f32x4 nkk = *(const LAS f32x4*)(pn), nwr = *(const LAS f32x4*)(pn + 2048), nw = *(const LAS f32x4*)(pn + 4096), nk = *(const LAS f32x4*)(pn + 6144), na = *(const LAS f32x4*)(pn + 8192);
;                 const float nv0 = pv[tn * 32], nv1 = pv[tn * 32 + 4]; const f32x2 nsc = *(const LAS f32x2*)(ps + 2 * tn);
;                 float sa[2], yp[2];
; #pragma unroll
;                 for (int c = 0; c < 2; ++c) { const f32x2 pa = S23[c] * kk4.hi + S01[c] * kk4.lo, pb = S23[c] * wr4.hi + S01[c] * wr4.lo; sa[c] = pa.x + pa.y; yp[c] = pb.x + pb.y; }
; #pragma unroll
;                 for (int c = 0; c < 2; ++c) { sa[c] = sum16(sa[c]); yp[c] += dppf<0xB1>(yp[c]); yp[c] += dppf<0x4E>(yp[c]); }
; #pragma unroll
;                 for (int c = 0; c < 2; ++c) {
;                     S01[c] = S01[c] * w4.lo + (k4.lo * vv[c] - a4.lo * sa[c]);
;                     S23[c] = S23[c] * w4.hi + (k4.hi * vv[c] - a4.hi * sa[c]);
;                     py[(t * 32 + 4 * c) * 4] = yp[c] + 0.25f * (vv[c] * sc.x - sa[c] * sc.y);
;                 }
;                 kk4 = nkk; wr4 = nwr; w4 = nw; k4 = nk; a4 = na; vv[0] = nv0; vv[1] = nv1; sc = nsc;
;             }
	v_pk_mul_f32 v[64:65], v[2:3], v[16:17] op_sel_hi:[1,0]
	v_pk_mul_f32 v[66:67], v[2:3], v[20:21] op_sel_hi:[1,0]
	v_pk_mul_f32 v[68:69], v[36:37], v[28:29] op_sel_hi:[1,0]
	v_pk_fma_f32 v[64:65], v[4:5], v[16:17], v[64:65] op_sel:[0,1,0] op_sel_hi:[1,1,1]
	v_pk_fma_f32 v[66:67], v[4:5], v[20:21], v[66:67] op_sel:[0,1,0] op_sel_hi:[1,1,1]
	v_pk_mul_f32 v[70:71], v[36:37], v[28:29] op_sel:[0,1] op_sel_hi:[1,1]
	v_pk_fma_f32 v[64:65], v[6:7], v[18:19], v[64:65] op_sel_hi:[1,0,1]
	v_pk_fma_f32 v[66:67], v[6:7], v[22:23], v[66:67] op_sel_hi:[1,0,1]
	v_pk_mul_f32 v[72:73], v[36:37], v[30:31] op_sel_hi:[1,0]
	v_pk_fma_f32 v[64:65], v[8:9], v[18:19], v[64:65] op_sel:[0,1,0] op_sel_hi:[1,1,1]
	v_pk_fma_f32 v[66:67], v[8:9], v[22:23], v[66:67] op_sel:[0,1,0] op_sel_hi:[1,1,1]
	v_pk_mul_f32 v[74:75], v[36:37], v[30:31] op_sel:[0,1] op_sel_hi:[1,1]
	ds_read_b128 v[40:43], v10 offset:3328
	v_add_f32_dpp v78, v65, v64 quad_perm:[1,0,3,2] row_mask:0xf bank_mask:0xf bound_ctrl:1
	ds_read_b128 v[44:47], v10 offset:11520
	ds_read_b128 v[48:51], v10 offset:19712
	v_pk_fma_f32 v[68:69], v[2:3], v[24:25], v[68:69] op_sel_hi:[1,0,1]
	v_add_f32_dpp v79, v78, v78 quad_perm:[3,2,1,0] row_mask:0xf bank_mask:0xf bound_ctrl:1
	ds_read_b128 v[52:55], v10 offset:27904
	ds_read_b128 v[56:59], v10 offset:36096
	v_pk_fma_f32 v[70:71], v[4:5], v[24:25], v[70:71] op_sel:[0,1,0] op_sel_hi:[1,1,1]
	v_add_f32_dpp v80, v79, v79 row_half_mirror row_mask:0xf bank_mask:0xf bound_ctrl:1
	ds_read_b32 v60, v11 offset:42624
	ds_read_b32 v61, v12 offset:42624
	v_pk_fma_f32 v[72:73], v[6:7], v[26:27], v[72:73] op_sel_hi:[1,0,1]
	v_add_f32_dpp v76, v80, v80 row_mirror row_mask:0xf bank_mask:0xf bound_ctrl:1
	ds_read_b64 v[62:63], v13 offset:45160
	v_pk_fma_f32 v[74:75], v[8:9], v[26:27], v[74:75] op_sel:[0,1,0] op_sel_hi:[1,1,1]
	v_mul_f32_e32 v83, v36, v38
	v_mov_b32_dpp v77, v76 quad_perm:[1,0,3,2] row_mask:0xf bank_mask:0xf bound_ctrl:1
	v_add_f32_dpp v81, v67, v66 quad_perm:[1,0,3,2] row_mask:0xf bank_mask:0xf bound_ctrl:1
	v_pk_fma_f32 v[2:3], v[32:33], v[76:77], v[68:69] op_sel_hi:[0,1,1] neg_lo:[1,0,0] neg_hi:[1,0,0]
	v_pk_fma_f32 v[4:5], v[32:33], v[76:77], v[70:71] op_sel:[1,0,0] op_sel_hi:[1,1,1] neg_lo:[1,0,0] neg_hi:[1,0,0]
	v_pk_fma_f32 v[6:7], v[34:35], v[76:77], v[72:73] op_sel_hi:[0,1,1] neg_lo:[1,0,0] neg_hi:[1,0,0]
	v_pk_fma_f32 v[8:9], v[34:35], v[76:77], v[74:75] op_sel:[1,0,0] op_sel_hi:[1,1,1] neg_lo:[1,0,0] neg_hi:[1,0,0]
	v_fma_f32 v83, -v76, v39, v83
	v_add_f32_dpp v82, v81, v81 quad_perm:[3,2,1,0] row_mask:0xf bank_mask:0xf bound_ctrl:1
	v_fmac_f32_e32 v82, 0x3e800000, v83
	ds_write_b32 v14, v82 offset:6144
	s_waitcnt lgkmcnt(1)
	v_pk_mul_f32 v[64:65], v[2:3], v[40:41] op_sel_hi:[1,0]
	v_pk_mul_f32 v[66:67], v[2:3], v[44:45] op_sel_hi:[1,0]
	v_pk_mul_f32 v[68:69], v[60:61], v[52:53] op_sel_hi:[1,0]
	v_pk_fma_f32 v[64:65], v[4:5], v[40:41], v[64:65] op_sel:[0,1,0] op_sel_hi:[1,1,1]
	v_pk_fma_f32 v[66:67], v[4:5], v[44:45], v[66:67] op_sel:[0,1,0] op_sel_hi:[1,1,1]
	v_pk_mul_f32 v[70:71], v[60:61], v[52:53] op_sel:[0,1] op_sel_hi:[1,1]
	v_pk_fma_f32 v[64:65], v[6:7], v[42:43], v[64:65] op_sel_hi:[1,0,1]
	v_pk_fma_f32 v[66:67], v[6:7], v[46:47], v[66:67] op_sel_hi:[1,0,1]
	v_pk_mul_f32 v[72:73], v[60:61], v[54:55] op_sel_hi:[1,0]
	v_pk_fma_f32 v[64:65], v[8:9], v[42:43], v[64:65] op_sel:[0,1,0] op_sel_hi:[1,1,1]
	v_pk_fma_f32 v[66:67], v[8:9], v[46:47], v[66:67] op_sel:[0,1,0] op_sel_hi:[1,1,1]
	v_pk_mul_f32 v[74:75], v[60:61], v[54:55] op_sel:[0,1] op_sel_hi:[1,1]
	ds_read_b128 v[16:19], v10 offset:3584
	v_add_f32_dpp v78, v65, v64 quad_perm:[1,0,3,2] row_mask:0xf bank_mask:0xf bound_ctrl:1
	ds_read_b128 v[20:23], v10 offset:11776
	ds_read_b128 v[24:27], v10 offset:19968
	v_pk_fma_f32 v[68:69], v[2:3], v[48:49], v[68:69] op_sel_hi:[1,0,1]
	v_add_f32_dpp v79, v78, v78 quad_perm:[3,2,1,0] row_mask:0xf bank_mask:0xf bound_ctrl:1
	ds_read_b128 v[28:31], v10 offset:28160
	ds_read_b128 v[32:35], v10 offset:36352
	v_pk_fma_f32 v[70:71], v[4:5], v[48:49], v[70:71] op_sel:[0,1,0] op_sel_hi:[1,1,1]
	v_add_f32_dpp v80, v79, v79 row_half_mirror row_mask:0xf bank_mask:0xf bound_ctrl:1
	ds_read_b32 v36, v11 offset:42752
	ds_read_b32 v37, v12 offset:42752
	v_pk_fma_f32 v[72:73], v[6:7], v[50:51], v[72:73] op_sel_hi:[1,0,1]
	v_add_f32_dpp v76, v80, v80 row_mirror row_mask:0xf bank_mask:0xf bound_ctrl:1
	ds_read_b64 v[38:39], v13 offset:45168
	v_pk_fma_f32 v[74:75], v[8:9], v[50:51], v[74:75] op_sel:[0,1,0] op_sel_hi:[1,1,1]
	v_mul_f32_e32 v83, v60, v62
	v_mov_b32_dpp v77, v76 quad_perm:[1,0,3,2] row_mask:0xf bank_mask:0xf bound_ctrl:1
	v_add_f32_dpp v81, v67, v66 quad_perm:[1,0,3,2] row_mask:0xf bank_mask:0xf bound_ctrl:1
	v_pk_fma_f32 v[2:3], v[56:57], v[76:77], v[68:69] op_sel_hi:[0,1,1] neg_lo:[1,0,0] neg_hi:[1,0,0]
	v_pk_fma_f32 v[4:5], v[56:57], v[76:77], v[70:71] op_sel:[1,0,0] op_sel_hi:[1,1,1] neg_lo:[1,0,0] neg_hi:[1,0,0]
	v_pk_fma_f32 v[6:7], v[58:59], v[76:77], v[72:73] op_sel_hi:[0,1,1] neg_lo:[1,0,0] neg_hi:[1,0,0]
	v_pk_fma_f32 v[8:9], v[58:59], v[76:77], v[74:75] op_sel:[1,0,0] op_sel_hi:[1,1,1] neg_lo:[1,0,0] neg_hi:[1,0,0]
	v_fma_f32 v83, -v76, v63, v83
	v_add_f32_dpp v82, v81, v81 quad_perm:[3,2,1,0] row_mask:0xf bank_mask:0xf bound_ctrl:1
	v_fmac_f32_e32 v82, 0x3e800000, v83
	ds_write_b32 v14, v82 offset:6656
	s_waitcnt lgkmcnt(1)
; #define LAS __attribute__((address_space(3)))
; template <int CTRL> __device__ __forceinline__ float dppf(float x) { return __builtin_bit_cast(float, __builtin_amdgcn_mov_dpp(__builtin_bit_cast(int, x), CTRL, 0xf, 0xf, true)); }
; __device__ __forceinline__ float sum16(float x) { x = sum8(x); x += dppf<0x140>(x); return x; }
; __device__ __forceinline__ void rwkv_item(LAS unsigned char* lds, int l, const bf16_t* PROJ, const bf16_t* LO, bf16_t* YR, float* BON, int b, int h, int qv) {
;     ...
;             for (int t = 0; t < CH; ++t) {
;                 const int tn = (t + 1) & (CH - 1);
;                 const LAS float* pn = pk + tn * 64;
;                 const f32x4 nkk = *(const LAS f32x4*)(pn), nwr = *(const LAS f32x4*)(pn + 2048), nw = *(const LAS f32x4*)(pn + 4096), nk = *(const LAS f32x4*)(pn + 6144), na = *(const LAS f32x4*)(pn + 8192);
;                 const float nv0 = pv[tn * 32], nv1 = pv[tn * 32 + 4]; const f32x2 nsc = *(const LAS f32x2*)(ps + 2 * tn);
;                 float sa[2], yp[2];
; #pragma unroll
;                 for (int c = 0; c < 2; ++c) { const f32x2 pa = S23[c] * kk4.hi + S01[c] * kk4.lo, pb = S23[c] * wr4.hi + S01[c] * wr4.lo; sa[c] = pa.x + pa.y; yp[c] = pb.x + pb.y; }
; #pragma unroll
;                 for (int c = 0; c < 2; ++c) { sa[c] = sum16(sa[c]); yp[c] += dppf<0xB1>(yp[c]); yp[c] += dppf<0x4E>(yp[c]); }
; #pragma unroll
;                 for (int c = 0; c < 2; ++c) {
;                     S01[c] = S01[c] * w4.lo + (k4.lo * vv[c] - a4.lo * sa[c]);
;                     S23[c] = S23[c] * w4.hi + (k4.hi * vv[c] - a4.hi * sa[c]);
;                     py[(t * 32 + 4 * c) * 4] = yp[c] + 0.25f * (vv[c] * sc.x - sa[c] * sc.y);
;                 }
;                 kk4 = nkk; wr4 = nwr; w4 = nw; k4 = nk; a4 = na; vv[0] = nv0; vv[1] = nv1; sc = nsc;
;             }
	v_pk_mul_f32 v[64:65], v[2:3], v[16:17] op_sel_hi:[1,0]
	v_pk_mul_f32 v[66:67], v[2:3], v[20:21] op_sel_hi:[1,0]
	v_pk_mul_f32 v[68:69], v[36:37], v[28:29] op_sel_hi:[1,0]
	v_pk_fma_f32 v[64:65], v[4:5], v[16:17], v[64:65] op_sel:[0,1,0] op_sel_hi:[1,1,1]
	v_pk_fma_f32 v[66:67], v[4:5], v[20:21], v[66:67] op_sel:[0,1,0] op_sel_hi:[1,1,1]
	v_pk_mul_f32 v[70:71], v[36:37], v[28:29] op_sel:[0,1] op_sel_hi:[1,1]
	v_pk_fma_f32 v[64:65], v[6:7], v[18:19], v[64:65] op_sel_hi:[1,0,1]
	v_pk_fma_f32 v[66:67], v[6:7], v[22:23], v[66:67] op_sel_hi:[1,0,1]
	v_pk_mul_f32 v[72:73], v[36:37], v[30:31] op_sel_hi:[1,0]
	v_pk_fma_f32 v[64:65], v[8:9], v[18:19], v[64:65] op_sel:[0,1,0] op_sel_hi:[1,1,1]
	v_pk_fma_f32 v[66:67], v[8:9], v[22:23], v[66:67] op_sel:[0,1,0] op_sel_hi:[1,1,1]
	v_pk_mul_f32 v[74:75], v[36:37], v[30:31] op_sel:[0,1] op_sel_hi:[1,1]
	ds_read_b128 v[40:43], v10 offset:3840
	v_add_f32_dpp v78, v65, v64 quad_perm:[1,0,3,2] row_mask:0xf bank_mask:0xf bound_ctrl:1
	ds_read_b128 v[44:47], v10 offset:12032
	ds_read_b128 v[48:51], v10 offset:20224
	v_pk_fma_f32 v[68:69], v[2:3], v[24:25], v[68:69] op_sel_hi:[1,0,1]
	v_add_f32_dpp v79, v78, v78 quad_perm:[3,2,1,0] row_mask:0xf bank_mask:0xf bound_ctrl:1
	ds_read_b128 v[52:55], v10 offset:28416
	ds_read_b128 v[56:59], v10 offset:36608
	v_pk_fma_f32 v[70:71], v[4:5], v[24:25], v[70:71] op_sel:[0,1,0] op_sel_hi:[1,1,1]
	v_add_f32_dpp v80, v79, v79 row_half_mirror row_mask:0xf bank_mask:0xf bound_ctrl:1
	ds_read_b32 v60, v11 offset:42880
	ds_read_b32 v61, v12 offset:42880
	v_pk_fma_f32 v[72:73], v[6:7], v[26:27], v[72:73] op_sel_hi:[1,0,1]
	v_add_f32_dpp v76, v80, v80 row_mirror row_mask:0xf bank_mask:0xf bound_ctrl:1
	ds_read_b64 v[62:63], v13 offset:45176
	v_pk_fma_f32 v[74:75], v[8:9], v[26:27], v[74:75] op_sel:[0,1,0] op_sel_hi:[1,1,1]
	v_mul_f32_e32 v83, v36, v38
	v_mov_b32_dpp v77, v76 quad_perm:[1,0,3,2] row_mask:0xf bank_mask:0xf bound_ctrl:1
	v_add_f32_dpp v81, v67, v66 quad_perm:[1,0,3,2] row_mask:0xf bank_mask:0xf bound_ctrl:1
	v_pk_fma_f32 v[2:3], v[32:33], v[76:77], v[68:69] op_sel_hi:[0,1,1] neg_lo:[1,0,0] neg_hi:[1,0,0]
	v_pk_fma_f32 v[4:5], v[32:33], v[76:77], v[70:71] op_sel:[1,0,0] op_sel_hi:[1,1,1] neg_lo:[1,0,0] neg_hi:[1,0,0]
	v_pk_fma_f32 v[6:7], v[34:35], v[76:77], v[72:73] op_sel_hi:[0,1,1] neg_lo:[1,0,0] neg_hi:[1,0,0]
	v_pk_fma_f32 v[8:9], v[34:35], v[76:77], v[74:75] op_sel:[1,0,0] op_sel_hi:[1,1,1] neg_lo:[1,0,0] neg_hi:[1,0,0]
	v_fma_f32 v83, -v76, v39, v83
	v_add_f32_dpp v82, v81, v81 quad_perm:[3,2,1,0] row_mask:0xf bank_mask:0xf bound_ctrl:1
	v_fmac_f32_e32 v82, 0x3e800000, v83
	ds_write_b32 v14, v82 offset:7168
	s_waitcnt lgkmcnt(1)
	v_pk_mul_f32 v[64:65], v[2:3], v[40:41] op_sel_hi:[1,0]
	v_pk_mul_f32 v[66:67], v[2:3], v[44:45] op_sel_hi:[1,0]
	v_pk_mul_f32 v[68:69], v[60:61], v[52:53] op_sel_hi:[1,0]
	v_pk_fma_f32 v[64:65], v[4:5], v[40:41], v[64:65] op_sel:[0,1,0] op_sel_hi:[1,1,1]
	v_pk_fma_f32 v[66:67], v[4:5], v[44:45], v[66:67] op_sel:[0,1,0] op_sel_hi:[1,1,1]
	v_pk_mul_f32 v[70:71], v[60:61], v[52:53] op_sel:[0,1] op_sel_hi:[1,1]
	v_pk_fma_f32 v[64:65], v[6:7], v[42:43], v[64:65] op_sel_hi:[1,0,1]
	v_pk_fma_f32 v[66:67], v[6:7], v[46:47], v[66:67] op_sel_hi:[1,0,1]
	v_pk_mul_f32 v[72:73], v[60:61], v[54:55] op_sel_hi:[1,0]
	v_pk_fma_f32 v[64:65], v[8:9], v[42:43], v[64:65] op_sel:[0,1,0] op_sel_hi:[1,1,1]
	v_pk_fma_f32 v[66:67], v[8:9], v[46:47], v[66:67] op_sel:[0,1,0] op_sel_hi:[1,1,1]
	v_pk_mul_f32 v[74:75], v[60:61], v[54:55] op_sel:[0,1] op_sel_hi:[1,1]
	ds_read_b128 v[16:19], v10 offset:4096
	v_add_f32_dpp v78, v65, v64 quad_perm:[1,0,3,2] row_mask:0xf bank_mask:0xf bound_ctrl:1
	ds_read_b128 v[20:23], v10 offset:12288
	ds_read_b128 v[24:27], v10 offset:20480
	v_pk_fma_f32 v[68:69], v[2:3], v[48:49], v[68:69] op_sel_hi:[1,0,1]
	v_add_f32_dpp v79, v78, v78 quad_perm:[3,2,1,0] row_mask:0xf bank_mask:0xf bound_ctrl:1
	ds_read_b128 v[28:31], v10 offset:28672
	ds_read_b128 v[32:35], v10 offset:36864
	v_pk_fma_f32 v[70:71], v[4:5], v[48:49], v[70:71] op_sel:[0,1,0] op_sel_hi:[1,1,1]
	v_add_f32_dpp v80, v79, v79 row_half_mirror row_mask:0xf bank_mask:0xf bound_ctrl:1
	ds_read_b32 v36, v11 offset:43008
	ds_read_b32 v37, v12 offset:43008
	v_pk_fma_f32 v[72:73], v[6:7], v[50:51], v[72:73] op_sel_hi:[1,0,1]
	v_add_f32_dpp v76, v80, v80 row_mirror row_mask:0xf bank_mask:0xf bound_ctrl:1
	ds_read_b64 v[38:39], v13 offset:45184
	v_pk_fma_f32 v[74:75], v[8:9], v[50:51], v[74:75] op_sel:[0,1,0] op_sel_hi:[1,1,1]
	v_mul_f32_e32 v83, v60, v62
	v_mov_b32_dpp v77, v76 quad_perm:[1,0,3,2] row_mask:0xf bank_mask:0xf bound_ctrl:1
	v_add_f32_dpp v81, v67, v66 quad_perm:[1,0,3,2] row_mask:0xf bank_mask:0xf bound_ctrl:1
	v_pk_fma_f32 v[2:3], v[56:57], v[76:77], v[68:69] op_sel_hi:[0,1,1] neg_lo:[1,0,0] neg_hi:[1,0,0]
	v_pk_fma_f32 v[4:5], v[56:57], v[76:77], v[70:71] op_sel:[1,0,0] op_sel_hi:[1,1,1] neg_lo:[1,0,0] neg_hi:[1,0,0]
	v_pk_fma_f32 v[6:7], v[58:59], v[76:77], v[72:73] op_sel_hi:[0,1,1] neg_lo:[1,0,0] neg_hi:[1,0,0]
	v_pk_fma_f32 v[8:9], v[58:59], v[76:77], v[74:75] op_sel:[1,0,0] op_sel_hi:[1,1,1] neg_lo:[1,0,0] neg_hi:[1,0,0]
	v_fma_f32 v83, -v76, v63, v83
	v_add_f32_dpp v82, v81, v81 quad_perm:[3,2,1,0] row_mask:0xf bank_mask:0xf bound_ctrl:1
	v_fmac_f32_e32 v82, 0x3e800000, v83
	ds_write_b32 v14, v82 offset:7680
	s_waitcnt lgkmcnt(1)
; #define LAS __attribute__((address_space(3)))
; template <int CTRL> __device__ __forceinline__ float dppf(float x) { return __builtin_bit_cast(float, __builtin_amdgcn_mov_dpp(__builtin_bit_cast(int, x), CTRL, 0xf, 0xf, true)); }
; __device__ __forceinline__ float sum16(float x) { x = sum8(x); x += dppf<0x140>(x); return x; }
; __device__ __forceinline__ void rwkv_item(LAS unsigned char* lds, int l, const bf16_t* PROJ, const bf16_t* LO, bf16_t* YR, float* BON, int b, int h, int qv) {
;     ...
;             for (int t = 0; t < CH; ++t) {
;                 const int tn = (t + 1) & (CH - 1);
;                 const LAS float* pn = pk + tn * 64;
;                 const f32x4 nkk = *(const LAS f32x4*)(pn), nwr = *(const LAS f32x4*)(pn + 2048), nw = *(const LAS f32x4*)(pn + 4096), nk = *(const LAS f32x4*)(pn + 6144), na = *(const LAS f32x4*)(pn + 8192);
;                 const float nv0 = pv[tn * 32], nv1 = pv[tn * 32 + 4]; const f32x2 nsc = *(const LAS f32x2*)(ps + 2 * tn);
;                 float sa[2], yp[2];
; #pragma unroll
;                 for (int c = 0; c < 2; ++c) { const f32x2 pa = S23[c] * kk4.hi + S01[c] * kk4.lo, pb = S23[c] * wr4.hi + S01[c] * wr4.lo; sa[c] = pa.x + pa.y; yp[c] = pb.x + pb.y; }
; #pragma unroll
;                 for (int c = 0; c < 2; ++c) { sa[c] = sum16(sa[c]); yp[c] += dppf<0xB1>(yp[c]); yp[c] += dppf<0x4E>(yp[c]); }
; #pragma unroll
;                 for (int c = 0; c < 2; ++c) {
;                     S01[c] = S01[c] * w4.lo + (k4.lo * vv[c] - a4.lo * sa[c]);
;                     S23[c] = S23[c] * w4.hi + (k4.hi * vv[c] - a4.hi * sa[c]);
;                     py[(t * 32 + 4 * c) * 4] = yp[c] + 0.25f * (vv[c] * sc.x - sa[c] * sc.y);
;                 }
;                 kk4 = nkk; wr4 = nwr; w4 = nw; k4 = nk; a4 = na; vv[0] = nv0; vv[1] = nv1; sc = nsc;
;             }
	v_pk_mul_f32 v[64:65], v[2:3], v[16:17] op_sel_hi:[1,0]
	v_pk_mul_f32 v[66:67], v[2:3], v[20:21] op_sel_hi:[1,0]
	v_pk_mul_f32 v[68:69], v[36:37], v[28:29] op_sel_hi:[1,0]
	v_pk_fma_f32 v[64:65], v[4:5], v[16:17], v[64:65] op_sel:[0,1,0] op_sel_hi:[1,1,1]
	v_pk_fma_f32 v[66:67], v[4:5], v[20:21], v[66:67] op_sel:[0,1,0] op_sel_hi:[1,1,1]
	v_pk_mul_f32 v[70:71], v[36:37], v[28:29] op_sel:[0,1] op_sel_hi:[1,1]
	v_pk_fma_f32 v[64:65], v[6:7], v[18:19], v[64:65] op_sel_hi:[1,0,1]
	v_pk_fma_f32 v[66:67], v[6:7], v[22:23], v[66:67] op_sel_hi:[1,0,1]
	v_pk_mul_f32 v[72:73], v[36:37], v[30:31] op_sel_hi:[1,0]
	v_pk_fma_f32 v[64:65], v[8:9], v[18:19], v[64:65] op_sel:[0,1,0] op_sel_hi:[1,1,1]
	v_pk_fma_f32 v[66:67], v[8:9], v[22:23], v[66:67] op_sel:[0,1,0] op_sel_hi:[1,1,1]
	v_pk_mul_f32 v[74:75], v[36:37], v[30:31] op_sel:[0,1] op_sel_hi:[1,1]
	ds_read_b128 v[40:43], v10 offset:4352
	v_add_f32_dpp v78, v65, v64 quad_perm:[1,0,3,2] row_mask:0xf bank_mask:0xf bound_ctrl:1
	ds_read_b128 v[44:47], v10 offset:12544
	ds_read_b128 v[48:51], v10 offset:20736
	v_pk_fma_f32 v[68:69], v[2:3], v[24:25], v[68:69] op_sel_hi:[1,0,1]
	v_add_f32_dpp v79, v78, v78 quad_perm:[3,2,1,0] row_mask:0xf bank_mask:0xf bound_ctrl:1
	ds_read_b128 v[52:55], v10 offset:28928
	ds_read_b128 v[56:59], v10 offset:37120
	v_pk_fma_f32 v[70:71], v[4:5], v[24:25], v[70:71] op_sel:[0,1,0] op_sel_hi:[1,1,1]
	v_add_f32_dpp v80, v79, v79 row_half_mirror row_mask:0xf bank_mask:0xf bound_ctrl:1
	ds_read_b32 v60, v11 offset:43136
	ds_read_b32 v61, v12 offset:43136
	v_pk_fma_f32 v[72:73], v[6:7], v[26:27], v[72:73] op_sel_hi:[1,0,1]
	v_add_f32_dpp v76, v80, v80 row_mirror row_mask:0xf bank_mask:0xf bound_ctrl:1
	ds_read_b64 v[62:63], v13 offset:45192
	v_pk_fma_f32 v[74:75], v[8:9], v[26:27], v[74:75] op_sel:[0,1,0] op_sel_hi:[1,1,1]
	v_mul_f32_e32 v83, v36, v38
	v_mov_b32_dpp v77, v76 quad_perm:[1,0,3,2] row_mask:0xf bank_mask:0xf bound_ctrl:1
	v_add_f32_dpp v81, v67, v66 quad_perm:[1,0,3,2] row_mask:0xf bank_mask:0xf bound_ctrl:1
	v_pk_fma_f32 v[2:3], v[32:33], v[76:77], v[68:69] op_sel_hi:[0,1,1] neg_lo:[1,0,0] neg_hi:[1,0,0]
	v_pk_fma_f32 v[4:5], v[32:33], v[76:77], v[70:71] op_sel:[1,0,0] op_sel_hi:[1,1,1] neg_lo:[1,0,0] neg_hi:[1,0,0]
	v_pk_fma_f32 v[6:7], v[34:35], v[76:77], v[72:73] op_sel_hi:[0,1,1] neg_lo:[1,0,0] neg_hi:[1,0,0]
	v_pk_fma_f32 v[8:9], v[34:35], v[76:77], v[74:75] op_sel:[1,0,0] op_sel_hi:[1,1,1] neg_lo:[1,0,0] neg_hi:[1,0,0]
	v_fma_f32 v83, -v76, v39, v83
	v_add_f32_dpp v82, v81, v81 quad_perm:[3,2,1,0] row_mask:0xf bank_mask:0xf bound_ctrl:1
	v_fmac_f32_e32 v82, 0x3e800000, v83
	ds_write_b32 v14, v82 offset:8192
	s_waitcnt lgkmcnt(1)
	v_pk_mul_f32 v[64:65], v[2:3], v[40:41] op_sel_hi:[1,0]
	v_pk_mul_f32 v[66:67], v[2:3], v[44:45] op_sel_hi:[1,0]
	v_pk_mul_f32 v[68:69], v[60:61], v[52:53] op_sel_hi:[1,0]
	v_pk_fma_f32 v[64:65], v[4:5], v[40:41], v[64:65] op_sel:[0,1,0] op_sel_hi:[1,1,1]
	v_pk_fma_f32 v[66:67], v[4:5], v[44:45], v[66:67] op_sel:[0,1,0] op_sel_hi:[1,1,1]
	v_pk_mul_f32 v[70:71], v[60:61], v[52:53] op_sel:[0,1] op_sel_hi:[1,1]
	v_pk_fma_f32 v[64:65], v[6:7], v[42:43], v[64:65] op_sel_hi:[1,0,1]
	v_pk_fma_f32 v[66:67], v[6:7], v[46:47], v[66:67] op_sel_hi:[1,0,1]
	v_pk_mul_f32 v[72:73], v[60:61], v[54:55] op_sel_hi:[1,0]
	v_pk_fma_f32 v[64:65], v[8:9], v[42:43], v[64:65] op_sel:[0,1,0] op_sel_hi:[1,1,1]
	v_pk_fma_f32 v[66:67], v[8:9], v[46:47], v[66:67] op_sel:[0,1,0] op_sel_hi:[1,1,1]
	v_pk_mul_f32 v[74:75], v[60:61], v[54:55] op_sel:[0,1] op_sel_hi:[1,1]
	ds_read_b128 v[16:19], v10 offset:4608
	v_add_f32_dpp v78, v65, v64 quad_perm:[1,0,3,2] row_mask:0xf bank_mask:0xf bound_ctrl:1
	ds_read_b128 v[20:23], v10 offset:12800
	ds_read_b128 v[24:27], v10 offset:20992
	v_pk_fma_f32 v[68:69], v[2:3], v[48:49], v[68:69] op_sel_hi:[1,0,1]
	v_add_f32_dpp v79, v78, v78 quad_perm:[3,2,1,0] row_mask:0xf bank_mask:0xf bound_ctrl:1
	ds_read_b128 v[28:31], v10 offset:29184
	ds_read_b128 v[32:35], v10 offset:37376
	v_pk_fma_f32 v[70:71], v[4:5], v[48:49], v[70:71] op_sel:[0,1,0] op_sel_hi:[1,1,1]
	v_add_f32_dpp v80, v79, v79 row_half_mirror row_mask:0xf bank_mask:0xf bound_ctrl:1
	ds_read_b32 v36, v11 offset:43264
	ds_read_b32 v37, v12 offset:43264
	v_pk_fma_f32 v[72:73], v[6:7], v[50:51], v[72:73] op_sel_hi:[1,0,1]
	v_add_f32_dpp v76, v80, v80 row_mirror row_mask:0xf bank_mask:0xf bound_ctrl:1
	ds_read_b64 v[38:39], v13 offset:45200
	v_pk_fma_f32 v[74:75], v[8:9], v[50:51], v[74:75] op_sel:[0,1,0] op_sel_hi:[1,1,1]
	v_mul_f32_e32 v83, v60, v62
	v_mov_b32_dpp v77, v76 quad_perm:[1,0,3,2] row_mask:0xf bank_mask:0xf bound_ctrl:1
	v_add_f32_dpp v81, v67, v66 quad_perm:[1,0,3,2] row_mask:0xf bank_mask:0xf bound_ctrl:1
	v_pk_fma_f32 v[2:3], v[56:57], v[76:77], v[68:69] op_sel_hi:[0,1,1] neg_lo:[1,0,0] neg_hi:[1,0,0]
	v_pk_fma_f32 v[4:5], v[56:57], v[76:77], v[70:71] op_sel:[1,0,0] op_sel_hi:[1,1,1] neg_lo:[1,0,0] neg_hi:[1,0,0]
	v_pk_fma_f32 v[6:7], v[58:59], v[76:77], v[72:73] op_sel_hi:[0,1,1] neg_lo:[1,0,0] neg_hi:[1,0,0]
	v_pk_fma_f32 v[8:9], v[58:59], v[76:77], v[74:75] op_sel:[1,0,0] op_sel_hi:[1,1,1] neg_lo:[1,0,0] neg_hi:[1,0,0]
	v_fma_f32 v83, -v76, v63, v83
	v_add_f32_dpp v82, v81, v81 quad_perm:[3,2,1,0] row_mask:0xf bank_mask:0xf bound_ctrl:1
	v_fmac_f32_e32 v82, 0x3e800000, v83
	ds_write_b32 v14, v82 offset:8704
	s_waitcnt lgkmcnt(1)
; #define LAS __attribute__((address_space(3)))
; template <int CTRL> __device__ __forceinline__ float dppf(float x) { return __builtin_bit_cast(float, __builtin_amdgcn_mov_dpp(__builtin_bit_cast(int, x), CTRL, 0xf, 0xf, true)); }
; __device__ __forceinline__ float sum16(float x) { x = sum8(x); x += dppf<0x140>(x); return x; }
; __device__ __forceinline__ void rwkv_item(LAS unsigned char* lds, int l, const bf16_t* PROJ, const bf16_t* LO, bf16_t* YR, float* BON, int b, int h, int qv) {
;     ...
;             for (int t = 0; t < CH; ++t) {
;                 const int tn = (t + 1) & (CH - 1);
;                 const LAS float* pn = pk + tn * 64;
;                 const f32x4 nkk = *(const LAS f32x4*)(pn), nwr = *(const LAS f32x4*)(pn + 2048), nw = *(const LAS f32x4*)(pn + 4096), nk = *(const LAS f32x4*)(pn + 6144), na = *(const LAS f32x4*)(pn + 8192);
;                 const float nv0 = pv[tn * 32], nv1 = pv[tn * 32 + 4]; const f32x2 nsc = *(const LAS f32x2*)(ps + 2 * tn);
;                 float sa[2], yp[2];
; #pragma unroll
;                 for (int c = 0; c < 2; ++c) { const f32x2 pa = S23[c] * kk4.hi + S01[c] * kk4.lo, pb = S23[c] * wr4.hi + S01[c] * wr4.lo; sa[c] = pa.x + pa.y; yp[c] = pb.x + pb.y; }
; #pragma unroll
;                 for (int c = 0; c < 2; ++c) { sa[c] = sum16(sa[c]); yp[c] += dppf<0xB1>(yp[c]); yp[c] += dppf<0x4E>(yp[c]); }
; #pragma unroll
;                 for (int c = 0; c < 2; ++c) {
;                     S01[c] = S01[c] * w4.lo + (k4.lo * vv[c] - a4.lo * sa[c]);
;                     S23[c] = S23[c] * w4.hi + (k4.hi * vv[c] - a4.hi * sa[c]);
;                     py[(t * 32 + 4 * c) * 4] = yp[c] + 0.25f * (vv[c] * sc.x - sa[c] * sc.y);
;                 }
;                 kk4 = nkk; wr4 = nwr; w4 = nw; k4 = nk; a4 = na; vv[0] = nv0; vv[1] = nv1; sc = nsc;
;             }
	v_pk_mul_f32 v[64:65], v[2:3], v[16:17] op_sel_hi:[1,0]
	v_pk_mul_f32 v[66:67], v[2:3], v[20:21] op_sel_hi:[1,0]
	v_pk_mul_f32 v[68:69], v[36:37], v[28:29] op_sel_hi:[1,0]
	v_pk_fma_f32 v[64:65], v[4:5], v[16:17], v[64:65] op_sel:[0,1,0] op_sel_hi:[1,1,1]
	v_pk_fma_f32 v[66:67], v[4:5], v[20:21], v[66:67] op_sel:[0,1,0] op_sel_hi:[1,1,1]
	v_pk_mul_f32 v[70:71], v[36:37], v[28:29] op_sel:[0,1] op_sel_hi:[1,1]
	v_pk_fma_f32 v[64:65], v[6:7], v[18:19], v[64:65] op_sel_hi:[1,0,1]
	v_pk_fma_f32 v[66:67], v[6:7], v[22:23], v[66:67] op_sel_hi:[1,0,1]
	v_pk_mul_f32 v[72:73], v[36:37], v[30:31] op_sel_hi:[1,0]
	v_pk_fma_f32 v[64:65], v[8:9], v[18:19], v[64:65] op_sel:[0,1,0] op_sel_hi:[1,1,1]
	v_pk_fma_f32 v[66:67], v[8:9], v[22:23], v[66:67] op_sel:[0,1,0] op_sel_hi:[1,1,1]
	v_pk_mul_f32 v[74:75], v[36:37], v[30:31] op_sel:[0,1] op_sel_hi:[1,1]
	ds_read_b128 v[40:43], v10 offset:4864
	v_add_f32_dpp v78, v65, v64 quad_perm:[1,0,3,2] row_mask:0xf bank_mask:0xf bound_ctrl:1
	ds_read_b128 v[44:47], v10 offset:13056
	ds_read_b128 v[48:51], v10 offset:21248
	v_pk_fma_f32 v[68:69], v[2:3], v[24:25], v[68:69] op_sel_hi:[1,0,1]
	v_add_f32_dpp v79, v78, v78 quad_perm:[3,2,1,0] row_mask:0xf bank_mask:0xf bound_ctrl:1
	ds_read_b128 v[52:55], v10 offset:29440
	ds_read_b128 v[56:59], v10 offset:37632
	v_pk_fma_f32 v[70:71], v[4:5], v[24:25], v[70:71] op_sel:[0,1,0] op_sel_hi:[1,1,1]
	v_add_f32_dpp v80, v79, v79 row_half_mirror row_mask:0xf bank_mask:0xf bound_ctrl:1
	ds_read_b32 v60, v11 offset:43392
	ds_read_b32 v61, v12 offset:43392
	v_pk_fma_f32 v[72:73], v[6:7], v[26:27], v[72:73] op_sel_hi:[1,0,1]
	v_add_f32_dpp v76, v80, v80 row_mirror row_mask:0xf bank_mask:0xf bound_ctrl:1
	ds_read_b64 v[62:63], v13 offset:45208
	v_pk_fma_f32 v[74:75], v[8:9], v[26:27], v[74:75] op_sel:[0,1,0] op_sel_hi:[1,1,1]
	v_mul_f32_e32 v83, v36, v38
	v_mov_b32_dpp v77, v76 quad_perm:[1,0,3,2] row_mask:0xf bank_mask:0xf bound_ctrl:1
	v_add_f32_dpp v81, v67, v66 quad_perm:[1,0,3,2] row_mask:0xf bank_mask:0xf bound_ctrl:1
	v_pk_fma_f32 v[2:3], v[32:33], v[76:77], v[68:69] op_sel_hi:[0,1,1] neg_lo:[1,0,0] neg_hi:[1,0,0]
	v_pk_fma_f32 v[4:5], v[32:33], v[76:77], v[70:71] op_sel:[1,0,0] op_sel_hi:[1,1,1] neg_lo:[1,0,0] neg_hi:[1,0,0]
	v_pk_fma_f32 v[6:7], v[34:35], v[76:77], v[72:73] op_sel_hi:[0,1,1] neg_lo:[1,0,0] neg_hi:[1,0,0]
	v_pk_fma_f32 v[8:9], v[34:35], v[76:77], v[74:75] op_sel:[1,0,0] op_sel_hi:[1,1,1] neg_lo:[1,0,0] neg_hi:[1,0,0]
	v_fma_f32 v83, -v76, v39, v83
	v_add_f32_dpp v82, v81, v81 quad_perm:[3,2,1,0] row_mask:0xf bank_mask:0xf bound_ctrl:1
	v_fmac_f32_e32 v82, 0x3e800000, v83
	ds_write_b32 v14, v82 offset:9216
	s_waitcnt lgkmcnt(1)
	v_pk_mul_f32 v[64:65], v[2:3], v[40:41] op_sel_hi:[1,0]
	v_pk_mul_f32 v[66:67], v[2:3], v[44:45] op_sel_hi:[1,0]
	v_pk_mul_f32 v[68:69], v[60:61], v[52:53] op_sel_hi:[1,0]
	v_pk_fma_f32 v[64:65], v[4:5], v[40:41], v[64:65] op_sel:[0,1,0] op_sel_hi:[1,1,1]
	v_pk_fma_f32 v[66:67], v[4:5], v[44:45], v[66:67] op_sel:[0,1,0] op_sel_hi:[1,1,1]
	v_pk_mul_f32 v[70:71], v[60:61], v[52:53] op_sel:[0,1] op_sel_hi:[1,1]
	v_pk_fma_f32 v[64:65], v[6:7], v[42:43], v[64:65] op_sel_hi:[1,0,1]
	v_pk_fma_f32 v[66:67], v[6:7], v[46:47], v[66:67] op_sel_hi:[1,0,1]
	v_pk_mul_f32 v[72:73], v[60:61], v[54:55] op_sel_hi:[1,0]
	v_pk_fma_f32 v[64:65], v[8:9], v[42:43], v[64:65] op_sel:[0,1,0] op_sel_hi:[1,1,1]
	v_pk_fma_f32 v[66:67], v[8:9], v[46:47], v[66:67] op_sel:[0,1,0] op_sel_hi:[1,1,1]
	v_pk_mul_f32 v[74:75], v[60:61], v[54:55] op_sel:[0,1] op_sel_hi:[1,1]
	ds_read_b128 v[16:19], v10 offset:5120
	v_add_f32_dpp v78, v65, v64 quad_perm:[1,0,3,2] row_mask:0xf bank_mask:0xf bound_ctrl:1
	ds_read_b128 v[20:23], v10 offset:13312
	ds_read_b128 v[24:27], v10 offset:21504
	v_pk_fma_f32 v[68:69], v[2:3], v[48:49], v[68:69] op_sel_hi:[1,0,1]
	v_add_f32_dpp v79, v78, v78 quad_perm:[3,2,1,0] row_mask:0xf bank_mask:0xf bound_ctrl:1
	ds_read_b128 v[28:31], v10 offset:29696
	ds_read_b128 v[32:35], v10 offset:37888
	v_pk_fma_f32 v[70:71], v[4:5], v[48:49], v[70:71] op_sel:[0,1,0] op_sel_hi:[1,1,1]
	v_add_f32_dpp v80, v79, v79 row_half_mirror row_mask:0xf bank_mask:0xf bound_ctrl:1
	ds_read_b32 v36, v11 offset:43520
	ds_read_b32 v37, v12 offset:43520
	v_pk_fma_f32 v[72:73], v[6:7], v[50:51], v[72:73] op_sel_hi:[1,0,1]
	v_add_f32_dpp v76, v80, v80 row_mirror row_mask:0xf bank_mask:0xf bound_ctrl:1
	ds_read_b64 v[38:39], v13 offset:45216
	v_pk_fma_f32 v[74:75], v[8:9], v[50:51], v[74:75] op_sel:[0,1,0] op_sel_hi:[1,1,1]
	v_mul_f32_e32 v83, v60, v62
	v_mov_b32_dpp v77, v76 quad_perm:[1,0,3,2] row_mask:0xf bank_mask:0xf bound_ctrl:1
	v_add_f32_dpp v81, v67, v66 quad_perm:[1,0,3,2] row_mask:0xf bank_mask:0xf bound_ctrl:1
	v_pk_fma_f32 v[2:3], v[56:57], v[76:77], v[68:69] op_sel_hi:[0,1,1] neg_lo:[1,0,0] neg_hi:[1,0,0]
	v_pk_fma_f32 v[4:5], v[56:57], v[76:77], v[70:71] op_sel:[1,0,0] op_sel_hi:[1,1,1] neg_lo:[1,0,0] neg_hi:[1,0,0]
	v_pk_fma_f32 v[6:7], v[58:59], v[76:77], v[72:73] op_sel_hi:[0,1,1] neg_lo:[1,0,0] neg_hi:[1,0,0]
	v_pk_fma_f32 v[8:9], v[58:59], v[76:77], v[74:75] op_sel:[1,0,0] op_sel_hi:[1,1,1] neg_lo:[1,0,0] neg_hi:[1,0,0]
	v_fma_f32 v83, -v76, v63, v83
	v_add_f32_dpp v82, v81, v81 quad_perm:[3,2,1,0] row_mask:0xf bank_mask:0xf bound_ctrl:1
	v_fmac_f32_e32 v82, 0x3e800000, v83
	ds_write_b32 v14, v82 offset:9728
	s_waitcnt lgkmcnt(1)
; #define LAS __attribute__((address_space(3)))
; template <int CTRL> __device__ __forceinline__ float dppf(float x) { return __builtin_bit_cast(float, __builtin_amdgcn_mov_dpp(__builtin_bit_cast(int, x), CTRL, 0xf, 0xf, true)); }
; __device__ __forceinline__ float sum16(float x) { x = sum8(x); x += dppf<0x140>(x); return x; }
; __device__ __forceinline__ void rwkv_item(LAS unsigned char* lds, int l, const bf16_t* PROJ, const bf16_t* LO, bf16_t* YR, float* BON, int b, int h, int qv) {
;     ...
;             for (int t = 0; t < CH; ++t) {
;                 const int tn = (t + 1) & (CH - 1);
;                 const LAS float* pn = pk + tn * 64;
;                 const f32x4 nkk = *(const LAS f32x4*)(pn), nwr = *(const LAS f32x4*)(pn + 2048), nw = *(const LAS f32x4*)(pn + 4096), nk = *(const LAS f32x4*)(pn + 6144), na = *(const LAS f32x4*)(pn + 8192);
;                 const float nv0 = pv[tn * 32], nv1 = pv[tn * 32 + 4]; const f32x2 nsc = *(const LAS f32x2*)(ps + 2 * tn);
;                 float sa[2], yp[2];
; #pragma unroll
;                 for (int c = 0; c < 2; ++c) { const f32x2 pa = S23[c] * kk4.hi + S01[c] * kk4.lo, pb = S23[c] * wr4.hi + S01[c] * wr4.lo; sa[c] = pa.x + pa.y; yp[c] = pb.x + pb.y; }
; #pragma unroll
;                 for (int c = 0; c < 2; ++c) { sa[c] = sum16(sa[c]); yp[c] += dppf<0xB1>(yp[c]); yp[c] += dppf<0x4E>(yp[c]); }
; #pragma unroll
;                 for (int c = 0; c < 2; ++c) {
;                     S01[c] = S01[c] * w4.lo + (k4.lo * vv[c] - a4.lo * sa[c]);
;                     S23[c] = S23[c] * w4.hi + (k4.hi * vv[c] - a4.hi * sa[c]);
;                     py[(t * 32 + 4 * c) * 4] = yp[c] + 0.25f * (vv[c] * sc.x - sa[c] * sc.y);
;                 }
;                 kk4 = nkk; wr4 = nwr; w4 = nw; k4 = nk; a4 = na; vv[0] = nv0; vv[1] = nv1; sc = nsc;
;             }
	v_pk_mul_f32 v[64:65], v[2:3], v[16:17] op_sel_hi:[1,0]
	v_pk_mul_f32 v[66:67], v[2:3], v[20:21] op_sel_hi:[1,0]
	v_pk_mul_f32 v[68:69], v[36:37], v[28:29] op_sel_hi:[1,0]
	v_pk_fma_f32 v[64:65], v[4:5], v[16:17], v[64:65] op_sel:[0,1,0] op_sel_hi:[1,1,1]
	v_pk_fma_f32 v[66:67], v[4:5], v[20:21], v[66:67] op_sel:[0,1,0] op_sel_hi:[1,1,1]
	v_pk_mul_f32 v[70:71], v[36:37], v[28:29] op_sel:[0,1] op_sel_hi:[1,1]
	v_pk_fma_f32 v[64:65], v[6:7], v[18:19], v[64:65] op_sel_hi:[1,0,1]
	v_pk_fma_f32 v[66:67], v[6:7], v[22:23], v[66:67] op_sel_hi:[1,0,1]
	v_pk_mul_f32 v[72:73], v[36:37], v[30:31] op_sel_hi:[1,0]
	v_pk_fma_f32 v[64:65], v[8:9], v[18:19], v[64:65] op_sel:[0,1,0] op_sel_hi:[1,1,1]
	v_pk_fma_f32 v[66:67], v[8:9], v[22:23], v[66:67] op_sel:[0,1,0] op_sel_hi:[1,1,1]
	v_pk_mul_f32 v[74:75], v[36:37], v[30:31] op_sel:[0,1] op_sel_hi:[1,1]
	ds_read_b128 v[40:43], v10 offset:5376
	v_add_f32_dpp v78, v65, v64 quad_perm:[1,0,3,2] row_mask:0xf bank_mask:0xf bound_ctrl:1
	ds_read_b128 v[44:47], v10 offset:13568
	ds_read_b128 v[48:51], v10 offset:21760
	v_pk_fma_f32 v[68:69], v[2:3], v[24:25], v[68:69] op_sel_hi:[1,0,1]
	v_add_f32_dpp v79, v78, v78 quad_perm:[3,2,1,0] row_mask:0xf bank_mask:0xf bound_ctrl:1
	ds_read_b128 v[52:55], v10 offset:29952
	ds_read_b128 v[56:59], v10 offset:38144
	v_pk_fma_f32 v[70:71], v[4:5], v[24:25], v[70:71] op_sel:[0,1,0] op_sel_hi:[1,1,1]
	v_add_f32_dpp v80, v79, v79 row_half_mirror row_mask:0xf bank_mask:0xf bound_ctrl:1
	ds_read_b32 v60, v11 offset:43648
	ds_read_b32 v61, v12 offset:43648
	v_pk_fma_f32 v[72:73], v[6:7], v[26:27], v[72:73] op_sel_hi:[1,0,1]
	v_add_f32_dpp v76, v80, v80 row_mirror row_mask:0xf bank_mask:0xf bound_ctrl:1
	ds_read_b64 v[62:63], v13 offset:45224
	v_pk_fma_f32 v[74:75], v[8:9], v[26:27], v[74:75] op_sel:[0,1,0] op_sel_hi:[1,1,1]
	v_mul_f32_e32 v83, v36, v38
	v_mov_b32_dpp v77, v76 quad_perm:[1,0,3,2] row_mask:0xf bank_mask:0xf bound_ctrl:1
	v_add_f32_dpp v81, v67, v66 quad_perm:[1,0,3,2] row_mask:0xf bank_mask:0xf bound_ctrl:1
	v_pk_fma_f32 v[2:3], v[32:33], v[76:77], v[68:69] op_sel_hi:[0,1,1] neg_lo:[1,0,0] neg_hi:[1,0,0]
	v_pk_fma_f32 v[4:5], v[32:33], v[76:77], v[70:71] op_sel:[1,0,0] op_sel_hi:[1,1,1] neg_lo:[1,0,0] neg_hi:[1,0,0]
	v_pk_fma_f32 v[6:7], v[34:35], v[76:77], v[72:73] op_sel_hi:[0,1,1] neg_lo:[1,0,0] neg_hi:[1,0,0]
	v_pk_fma_f32 v[8:9], v[34:35], v[76:77], v[74:75] op_sel:[1,0,0] op_sel_hi:[1,1,1] neg_lo:[1,0,0] neg_hi:[1,0,0]
	v_fma_f32 v83, -v76, v39, v83
	v_add_f32_dpp v82, v81, v81 quad_perm:[3,2,1,0] row_mask:0xf bank_mask:0xf bound_ctrl:1
	v_fmac_f32_e32 v82, 0x3e800000, v83
	ds_write_b32 v14, v82 offset:10240
	s_waitcnt lgkmcnt(1)
	v_pk_mul_f32 v[64:65], v[2:3], v[40:41] op_sel_hi:[1,0]
	v_pk_mul_f32 v[66:67], v[2:3], v[44:45] op_sel_hi:[1,0]
	v_pk_mul_f32 v[68:69], v[60:61], v[52:53] op_sel_hi:[1,0]
	v_pk_fma_f32 v[64:65], v[4:5], v[40:41], v[64:65] op_sel:[0,1,0] op_sel_hi:[1,1,1]
	v_pk_fma_f32 v[66:67], v[4:5], v[44:45], v[66:67] op_sel:[0,1,0] op_sel_hi:[1,1,1]
	v_pk_mul_f32 v[70:71], v[60:61], v[52:53] op_sel:[0,1] op_sel_hi:[1,1]
	v_pk_fma_f32 v[64:65], v[6:7], v[42:43], v[64:65] op_sel_hi:[1,0,1]
	v_pk_fma_f32 v[66:67], v[6:7], v[46:47], v[66:67] op_sel_hi:[1,0,1]
	v_pk_mul_f32 v[72:73], v[60:61], v[54:55] op_sel_hi:[1,0]
	v_pk_fma_f32 v[64:65], v[8:9], v[42:43], v[64:65] op_sel:[0,1,0] op_sel_hi:[1,1,1]
	v_pk_fma_f32 v[66:67], v[8:9], v[46:47], v[66:67] op_sel:[0,1,0] op_sel_hi:[1,1,1]
	v_pk_mul_f32 v[74:75], v[60:61], v[54:55] op_sel:[0,1] op_sel_hi:[1,1]
	ds_read_b128 v[16:19], v10 offset:5632
	v_add_f32_dpp v78, v65, v64 quad_perm:[1,0,3,2] row_mask:0xf bank_mask:0xf bound_ctrl:1
	ds_read_b128 v[20:23], v10 offset:13824
	ds_read_b128 v[24:27], v10 offset:22016
	v_pk_fma_f32 v[68:69], v[2:3], v[48:49], v[68:69] op_sel_hi:[1,0,1]
	v_add_f32_dpp v79, v78, v78 quad_perm:[3,2,1,0] row_mask:0xf bank_mask:0xf bound_ctrl:1
	ds_read_b128 v[28:31], v10 offset:30208
	ds_read_b128 v[32:35], v10 offset:38400
	v_pk_fma_f32 v[70:71], v[4:5], v[48:49], v[70:71] op_sel:[0,1,0] op_sel_hi:[1,1,1]
	v_add_f32_dpp v80, v79, v79 row_half_mirror row_mask:0xf bank_mask:0xf bound_ctrl:1
	ds_read_b32 v36, v11 offset:43776
	ds_read_b32 v37, v12 offset:43776
	v_pk_fma_f32 v[72:73], v[6:7], v[50:51], v[72:73] op_sel_hi:[1,0,1]
	v_add_f32_dpp v76, v80, v80 row_mirror row_mask:0xf bank_mask:0xf bound_ctrl:1
	ds_read_b64 v[38:39], v13 offset:45232
	v_pk_fma_f32 v[74:75], v[8:9], v[50:51], v[74:75] op_sel:[0,1,0] op_sel_hi:[1,1,1]
	v_mul_f32_e32 v83, v60, v62
	v_mov_b32_dpp v77, v76 quad_perm:[1,0,3,2] row_mask:0xf bank_mask:0xf bound_ctrl:1
	v_add_f32_dpp v81, v67, v66 quad_perm:[1,0,3,2] row_mask:0xf bank_mask:0xf bound_ctrl:1
	v_pk_fma_f32 v[2:3], v[56:57], v[76:77], v[68:69] op_sel_hi:[0,1,1] neg_lo:[1,0,0] neg_hi:[1,0,0]
	v_pk_fma_f32 v[4:5], v[56:57], v[76:77], v[70:71] op_sel:[1,0,0] op_sel_hi:[1,1,1] neg_lo:[1,0,0] neg_hi:[1,0,0]
	v_pk_fma_f32 v[6:7], v[58:59], v[76:77], v[72:73] op_sel_hi:[0,1,1] neg_lo:[1,0,0] neg_hi:[1,0,0]
	v_pk_fma_f32 v[8:9], v[58:59], v[76:77], v[74:75] op_sel:[1,0,0] op_sel_hi:[1,1,1] neg_lo:[1,0,0] neg_hi:[1,0,0]
	v_fma_f32 v83, -v76, v63, v83
	v_add_f32_dpp v82, v81, v81 quad_perm:[3,2,1,0] row_mask:0xf bank_mask:0xf bound_ctrl:1
	v_fmac_f32_e32 v82, 0x3e800000, v83
	ds_write_b32 v14, v82 offset:10752
	s_waitcnt lgkmcnt(1)
; #define LAS __attribute__((address_space(3)))
; template <int CTRL> __device__ __forceinline__ float dppf(float x) { return __builtin_bit_cast(float, __builtin_amdgcn_mov_dpp(__builtin_bit_cast(int, x), CTRL, 0xf, 0xf, true)); }
; __device__ __forceinline__ float sum16(float x) { x = sum8(x); x += dppf<0x140>(x); return x; }
; __device__ __forceinline__ void rwkv_item(LAS unsigned char* lds, int l, const bf16_t* PROJ, const bf16_t* LO, bf16_t* YR, float* BON, int b, int h, int qv) {
;     ...
;             for (int t = 0; t < CH; ++t) {
;                 const int tn = (t + 1) & (CH - 1);
;                 const LAS float* pn = pk + tn * 64;
;                 const f32x4 nkk = *(const LAS f32x4*)(pn), nwr = *(const LAS f32x4*)(pn + 2048), nw = *(const LAS f32x4*)(pn + 4096), nk = *(const LAS f32x4*)(pn + 6144), na = *(const LAS f32x4*)(pn + 8192);
;                 const float nv0 = pv[tn * 32], nv1 = pv[tn * 32 + 4]; const f32x2 nsc = *(const LAS f32x2*)(ps + 2 * tn);
;                 float sa[2], yp[2];
; #pragma unroll
;                 for (int c = 0; c < 2; ++c) { const f32x2 pa = S23[c] * kk4.hi + S01[c] * kk4.lo, pb = S23[c] * wr4.hi + S01[c] * wr4.lo; sa[c] = pa.x + pa.y; yp[c] = pb.x + pb.y; }
; #pragma unroll
;                 for (int c = 0; c < 2; ++c) { sa[c] = sum16(sa[c]); yp[c] += dppf<0xB1>(yp[c]); yp[c] += dppf<0x4E>(yp[c]); }
; #pragma unroll
;                 for (int c = 0; c < 2; ++c) {
;                     S01[c] = S01[c] * w4.lo + (k4.lo * vv[c] - a4.lo * sa[c]);
;                     S23[c] = S23[c] * w4.hi + (k4.hi * vv[c] - a4.hi * sa[c]);
;                     py[(t * 32 + 4 * c) * 4] = yp[c] + 0.25f * (vv[c] * sc.x - sa[c] * sc.y);
;                 }
;                 kk4 = nkk; wr4 = nwr; w4 = nw; k4 = nk; a4 = na; vv[0] = nv0; vv[1] = nv1; sc = nsc;
;             }
	v_pk_mul_f32 v[64:65], v[2:3], v[16:17] op_sel_hi:[1,0]
	v_pk_mul_f32 v[66:67], v[2:3], v[20:21] op_sel_hi:[1,0]
	v_pk_mul_f32 v[68:69], v[36:37], v[28:29] op_sel_hi:[1,0]
	v_pk_fma_f32 v[64:65], v[4:5], v[16:17], v[64:65] op_sel:[0,1,0] op_sel_hi:[1,1,1]
	v_pk_fma_f32 v[66:67], v[4:5], v[20:21], v[66:67] op_sel:[0,1,0] op_sel_hi:[1,1,1]
	v_pk_mul_f32 v[70:71], v[36:37], v[28:29] op_sel:[0,1] op_sel_hi:[1,1]
	v_pk_fma_f32 v[64:65], v[6:7], v[18:19], v[64:65] op_sel_hi:[1,0,1]
	v_pk_fma_f32 v[66:67], v[6:7], v[22:23], v[66:67] op_sel_hi:[1,0,1]
	v_pk_mul_f32 v[72:73], v[36:37], v[30:31] op_sel_hi:[1,0]
	v_pk_fma_f32 v[64:65], v[8:9], v[18:19], v[64:65] op_sel:[0,1,0] op_sel_hi:[1,1,1]
	v_pk_fma_f32 v[66:67], v[8:9], v[22:23], v[66:67] op_sel:[0,1,0] op_sel_hi:[1,1,1]
	v_pk_mul_f32 v[74:75], v[36:37], v[30:31] op_sel:[0,1] op_sel_hi:[1,1]
	ds_read_b128 v[40:43], v10 offset:5888
	v_add_f32_dpp v78, v65, v64 quad_perm:[1,0,3,2] row_mask:0xf bank_mask:0xf bound_ctrl:1
	ds_read_b128 v[44:47], v10 offset:14080
	ds_read_b128 v[48:51], v10 offset:22272
	v_pk_fma_f32 v[68:69], v[2:3], v[24:25], v[68:69] op_sel_hi:[1,0,1]
	v_add_f32_dpp v79, v78, v78 quad_perm:[3,2,1,0] row_mask:0xf bank_mask:0xf bound_ctrl:1
	ds_read_b128 v[52:55], v10 offset:30464
	ds_read_b128 v[56:59], v10 offset:38656
	v_pk_fma_f32 v[70:71], v[4:5], v[24:25], v[70:71] op_sel:[0,1,0] op_sel_hi:[1,1,1]
	v_add_f32_dpp v80, v79, v79 row_half_mirror row_mask:0xf bank_mask:0xf bound_ctrl:1
	ds_read_b32 v60, v11 offset:43904
	ds_read_b32 v61, v12 offset:43904
	v_pk_fma_f32 v[72:73], v[6:7], v[26:27], v[72:73] op_sel_hi:[1,0,1]
	v_add_f32_dpp v76, v80, v80 row_mirror row_mask:0xf bank_mask:0xf bound_ctrl:1
	ds_read_b64 v[62:63], v13 offset:45240
	v_pk_fma_f32 v[74:75], v[8:9], v[26:27], v[74:75] op_sel:[0,1,0] op_sel_hi:[1,1,1]
	v_mul_f32_e32 v83, v36, v38
	v_mov_b32_dpp v77, v76 quad_perm:[1,0,3,2] row_mask:0xf bank_mask:0xf bound_ctrl:1
	v_add_f32_dpp v81, v67, v66 quad_perm:[1,0,3,2] row_mask:0xf bank_mask:0xf bound_ctrl:1
	v_pk_fma_f32 v[2:3], v[32:33], v[76:77], v[68:69] op_sel_hi:[0,1,1] neg_lo:[1,0,0] neg_hi:[1,0,0]
	v_pk_fma_f32 v[4:5], v[32:33], v[76:77], v[70:71] op_sel:[1,0,0] op_sel_hi:[1,1,1] neg_lo:[1,0,0] neg_hi:[1,0,0]
	v_pk_fma_f32 v[6:7], v[34:35], v[76:77], v[72:73] op_sel_hi:[0,1,1] neg_lo:[1,0,0] neg_hi:[1,0,0]
	v_pk_fma_f32 v[8:9], v[34:35], v[76:77], v[74:75] op_sel:[1,0,0] op_sel_hi:[1,1,1] neg_lo:[1,0,0] neg_hi:[1,0,0]
	v_fma_f32 v83, -v76, v39, v83
	v_add_f32_dpp v82, v81, v81 quad_perm:[3,2,1,0] row_mask:0xf bank_mask:0xf bound_ctrl:1
	v_fmac_f32_e32 v82, 0x3e800000, v83
	ds_write_b32 v14, v82 offset:11264
	s_waitcnt lgkmcnt(1)
	v_pk_mul_f32 v[64:65], v[2:3], v[40:41] op_sel_hi:[1,0]
	v_pk_mul_f32 v[66:67], v[2:3], v[44:45] op_sel_hi:[1,0]
	v_pk_mul_f32 v[68:69], v[60:61], v[52:53] op_sel_hi:[1,0]
	v_pk_fma_f32 v[64:65], v[4:5], v[40:41], v[64:65] op_sel:[0,1,0] op_sel_hi:[1,1,1]
	v_pk_fma_f32 v[66:67], v[4:5], v[44:45], v[66:67] op_sel:[0,1,0] op_sel_hi:[1,1,1]
	v_pk_mul_f32 v[70:71], v[60:61], v[52:53] op_sel:[0,1] op_sel_hi:[1,1]
	v_pk_fma_f32 v[64:65], v[6:7], v[42:43], v[64:65] op_sel_hi:[1,0,1]
	v_pk_fma_f32 v[66:67], v[6:7], v[46:47], v[66:67] op_sel_hi:[1,0,1]
	v_pk_mul_f32 v[72:73], v[60:61], v[54:55] op_sel_hi:[1,0]
	v_pk_fma_f32 v[64:65], v[8:9], v[42:43], v[64:65] op_sel:[0,1,0] op_sel_hi:[1,1,1]
	v_pk_fma_f32 v[66:67], v[8:9], v[46:47], v[66:67] op_sel:[0,1,0] op_sel_hi:[1,1,1]
	v_pk_mul_f32 v[74:75], v[60:61], v[54:55] op_sel:[0,1] op_sel_hi:[1,1]
	ds_read_b128 v[16:19], v10 offset:6144
	v_add_f32_dpp v78, v65, v64 quad_perm:[1,0,3,2] row_mask:0xf bank_mask:0xf bound_ctrl:1
	ds_read_b128 v[20:23], v10 offset:14336
	ds_read_b128 v[24:27], v10 offset:22528
	v_pk_fma_f32 v[68:69], v[2:3], v[48:49], v[68:69] op_sel_hi:[1,0,1]
	v_add_f32_dpp v79, v78, v78 quad_perm:[3,2,1,0] row_mask:0xf bank_mask:0xf bound_ctrl:1
	ds_read_b128 v[28:31], v10 offset:30720
	ds_read_b128 v[32:35], v10 offset:38912
	v_pk_fma_f32 v[70:71], v[4:5], v[48:49], v[70:71] op_sel:[0,1,0] op_sel_hi:[1,1,1]
	v_add_f32_dpp v80, v79, v79 row_half_mirror row_mask:0xf bank_mask:0xf bound_ctrl:1
	ds_read_b32 v36, v11 offset:44032
	ds_read_b32 v37, v12 offset:44032
	v_pk_fma_f32 v[72:73], v[6:7], v[50:51], v[72:73] op_sel_hi:[1,0,1]
	v_add_f32_dpp v76, v80, v80 row_mirror row_mask:0xf bank_mask:0xf bound_ctrl:1
	ds_read_b64 v[38:39], v13 offset:45248
	v_pk_fma_f32 v[74:75], v[8:9], v[50:51], v[74:75] op_sel:[0,1,0] op_sel_hi:[1,1,1]
	v_mul_f32_e32 v83, v60, v62
	v_mov_b32_dpp v77, v76 quad_perm:[1,0,3,2] row_mask:0xf bank_mask:0xf bound_ctrl:1
	v_add_f32_dpp v81, v67, v66 quad_perm:[1,0,3,2] row_mask:0xf bank_mask:0xf bound_ctrl:1
	v_pk_fma_f32 v[2:3], v[56:57], v[76:77], v[68:69] op_sel_hi:[0,1,1] neg_lo:[1,0,0] neg_hi:[1,0,0]
	v_pk_fma_f32 v[4:5], v[56:57], v[76:77], v[70:71] op_sel:[1,0,0] op_sel_hi:[1,1,1] neg_lo:[1,0,0] neg_hi:[1,0,0]
	v_pk_fma_f32 v[6:7], v[58:59], v[76:77], v[72:73] op_sel_hi:[0,1,1] neg_lo:[1,0,0] neg_hi:[1,0,0]
	v_pk_fma_f32 v[8:9], v[58:59], v[76:77], v[74:75] op_sel:[1,0,0] op_sel_hi:[1,1,1] neg_lo:[1,0,0] neg_hi:[1,0,0]
	v_fma_f32 v83, -v76, v63, v83
	v_add_f32_dpp v82, v81, v81 quad_perm:[3,2,1,0] row_mask:0xf bank_mask:0xf bound_ctrl:1
	v_fmac_f32_e32 v82, 0x3e800000, v83
	ds_write_b32 v14, v82 offset:11776
	s_waitcnt lgkmcnt(1)
; #define LAS __attribute__((address_space(3)))
; template <int CTRL> __device__ __forceinline__ float dppf(float x) { return __builtin_bit_cast(float, __builtin_amdgcn_mov_dpp(__builtin_bit_cast(int, x), CTRL, 0xf, 0xf, true)); }
; __device__ __forceinline__ float sum16(float x) { x = sum8(x); x += dppf<0x140>(x); return x; }
; __device__ __forceinline__ void rwkv_item(LAS unsigned char* lds, int l, const bf16_t* PROJ, const bf16_t* LO, bf16_t* YR, float* BON, int b, int h, int qv) {
;     ...
;             for (int t = 0; t < CH; ++t) {
;                 const int tn = (t + 1) & (CH - 1);
;                 const LAS float* pn = pk + tn * 64;
;                 const f32x4 nkk = *(const LAS f32x4*)(pn), nwr = *(const LAS f32x4*)(pn + 2048), nw = *(const LAS f32x4*)(pn + 4096), nk = *(const LAS f32x4*)(pn + 6144), na = *(const LAS f32x4*)(pn + 8192);
;                 const float nv0 = pv[tn * 32], nv1 = pv[tn * 32 + 4]; const f32x2 nsc = *(const LAS f32x2*)(ps + 2 * tn);
;                 float sa[2], yp[2];
; #pragma unroll
;                 for (int c = 0; c < 2; ++c) { const f32x2 pa = S23[c] * kk4.hi + S01[c] * kk4.lo, pb = S23[c] * wr4.hi + S01[c] * wr4.lo; sa[c] = pa.x + pa.y; yp[c] = pb.x + pb.y; }
; #pragma unroll
;                 for (int c = 0; c < 2; ++c) { sa[c] = sum16(sa[c]); yp[c] += dppf<0xB1>(yp[c]); yp[c] += dppf<0x4E>(yp[c]); }
; #pragma unroll
;                 for (int c = 0; c < 2; ++c) {
;                     S01[c] = S01[c] * w4.lo + (k4.lo * vv[c] - a4.lo * sa[c]);
;                     S23[c] = S23[c] * w4.hi + (k4.hi * vv[c] - a4.hi * sa[c]);
;                     py[(t * 32 + 4 * c) * 4] = yp[c] + 0.25f * (vv[c] * sc.x - sa[c] * sc.y);
;                 }
;                 kk4 = nkk; wr4 = nwr; w4 = nw; k4 = nk; a4 = na; vv[0] = nv0; vv[1] = nv1; sc = nsc;
;             }
	v_pk_mul_f32 v[64:65], v[2:3], v[16:17] op_sel_hi:[1,0]
	v_pk_mul_f32 v[66:67], v[2:3], v[20:21] op_sel_hi:[1,0]
	v_pk_mul_f32 v[68:69], v[36:37], v[28:29] op_sel_hi:[1,0]
	v_pk_fma_f32 v[64:65], v[4:5], v[16:17], v[64:65] op_sel:[0,1,0] op_sel_hi:[1,1,1]
	v_pk_fma_f32 v[66:67], v[4:5], v[20:21], v[66:67] op_sel:[0,1,0] op_sel_hi:[1,1,1]
	v_pk_mul_f32 v[70:71], v[36:37], v[28:29] op_sel:[0,1] op_sel_hi:[1,1]
	v_pk_fma_f32 v[64:65], v[6:7], v[18:19], v[64:65] op_sel_hi:[1,0,1]
	v_pk_fma_f32 v[66:67], v[6:7], v[22:23], v[66:67] op_sel_hi:[1,0,1]
	v_pk_mul_f32 v[72:73], v[36:37], v[30:31] op_sel_hi:[1,0]
	v_pk_fma_f32 v[64:65], v[8:9], v[18:19], v[64:65] op_sel:[0,1,0] op_sel_hi:[1,1,1]
	v_pk_fma_f32 v[66:67], v[8:9], v[22:23], v[66:67] op_sel:[0,1,0] op_sel_hi:[1,1,1]
	v_pk_mul_f32 v[74:75], v[36:37], v[30:31] op_sel:[0,1] op_sel_hi:[1,1]
	ds_read_b128 v[40:43], v10 offset:6400
	v_add_f32_dpp v78, v65, v64 quad_perm:[1,0,3,2] row_mask:0xf bank_mask:0xf bound_ctrl:1
	ds_read_b128 v[44:47], v10 offset:14592
	ds_read_b128 v[48:51], v10 offset:22784
	v_pk_fma_f32 v[68:69], v[2:3], v[24:25], v[68:69] op_sel_hi:[1,0,1]
	v_add_f32_dpp v79, v78, v78 quad_perm:[3,2,1,0] row_mask:0xf bank_mask:0xf bound_ctrl:1
	ds_read_b128 v[52:55], v10 offset:30976
	ds_read_b128 v[56:59], v10 offset:39168
	v_pk_fma_f32 v[70:71], v[4:5], v[24:25], v[70:71] op_sel:[0,1,0] op_sel_hi:[1,1,1]
	v_add_f32_dpp v80, v79, v79 row_half_mirror row_mask:0xf bank_mask:0xf bound_ctrl:1
	ds_read_b32 v60, v11 offset:44160
	ds_read_b32 v61, v12 offset:44160
	v_pk_fma_f32 v[72:73], v[6:7], v[26:27], v[72:73] op_sel_hi:[1,0,1]
	v_add_f32_dpp v76, v80, v80 row_mirror row_mask:0xf bank_mask:0xf bound_ctrl:1
	ds_read_b64 v[62:63], v13 offset:45256
	v_pk_fma_f32 v[74:75], v[8:9], v[26:27], v[74:75] op_sel:[0,1,0] op_sel_hi:[1,1,1]
	v_mul_f32_e32 v83, v36, v38
	v_mov_b32_dpp v77, v76 quad_perm:[1,0,3,2] row_mask:0xf bank_mask:0xf bound_ctrl:1
	v_add_f32_dpp v81, v67, v66 quad_perm:[1,0,3,2] row_mask:0xf bank_mask:0xf bound_ctrl:1
	v_pk_fma_f32 v[2:3], v[32:33], v[76:77], v[68:69] op_sel_hi:[0,1,1] neg_lo:[1,0,0] neg_hi:[1,0,0]
	v_pk_fma_f32 v[4:5], v[32:33], v[76:77], v[70:71] op_sel:[1,0,0] op_sel_hi:[1,1,1] neg_lo:[1,0,0] neg_hi:[1,0,0]
	v_pk_fma_f32 v[6:7], v[34:35], v[76:77], v[72:73] op_sel_hi:[0,1,1] neg_lo:[1,0,0] neg_hi:[1,0,0]
	v_pk_fma_f32 v[8:9], v[34:35], v[76:77], v[74:75] op_sel:[1,0,0] op_sel_hi:[1,1,1] neg_lo:[1,0,0] neg_hi:[1,0,0]
	v_fma_f32 v83, -v76, v39, v83
	v_add_f32_dpp v82, v81, v81 quad_perm:[3,2,1,0] row_mask:0xf bank_mask:0xf bound_ctrl:1
	v_fmac_f32_e32 v82, 0x3e800000, v83
	ds_write_b32 v14, v82 offset:12288
	s_waitcnt lgkmcnt(1)
	v_pk_mul_f32 v[64:65], v[2:3], v[40:41] op_sel_hi:[1,0]
	v_pk_mul_f32 v[66:67], v[2:3], v[44:45] op_sel_hi:[1,0]
	v_pk_mul_f32 v[68:69], v[60:61], v[52:53] op_sel_hi:[1,0]
	v_pk_fma_f32 v[64:65], v[4:5], v[40:41], v[64:65] op_sel:[0,1,0] op_sel_hi:[1,1,1]
	v_pk_fma_f32 v[66:67], v[4:5], v[44:45], v[66:67] op_sel:[0,1,0] op_sel_hi:[1,1,1]
	v_pk_mul_f32 v[70:71], v[60:61], v[52:53] op_sel:[0,1] op_sel_hi:[1,1]
	v_pk_fma_f32 v[64:65], v[6:7], v[42:43], v[64:65] op_sel_hi:[1,0,1]
	v_pk_fma_f32 v[66:67], v[6:7], v[46:47], v[66:67] op_sel_hi:[1,0,1]
	v_pk_mul_f32 v[72:73], v[60:61], v[54:55] op_sel_hi:[1,0]
	v_pk_fma_f32 v[64:65], v[8:9], v[42:43], v[64:65] op_sel:[0,1,0] op_sel_hi:[1,1,1]
	v_pk_fma_f32 v[66:67], v[8:9], v[46:47], v[66:67] op_sel:[0,1,0] op_sel_hi:[1,1,1]
	v_pk_mul_f32 v[74:75], v[60:61], v[54:55] op_sel:[0,1] op_sel_hi:[1,1]
	ds_read_b128 v[16:19], v10 offset:6656
	v_add_f32_dpp v78, v65, v64 quad_perm:[1,0,3,2] row_mask:0xf bank_mask:0xf bound_ctrl:1
	ds_read_b128 v[20:23], v10 offset:14848
	ds_read_b128 v[24:27], v10 offset:23040
	v_pk_fma_f32 v[68:69], v[2:3], v[48:49], v[68:69] op_sel_hi:[1,0,1]
	v_add_f32_dpp v79, v78, v78 quad_perm:[3,2,1,0] row_mask:0xf bank_mask:0xf bound_ctrl:1
	ds_read_b128 v[28:31], v10 offset:31232
	ds_read_b128 v[32:35], v10 offset:39424
	v_pk_fma_f32 v[70:71], v[4:5], v[48:49], v[70:71] op_sel:[0,1,0] op_sel_hi:[1,1,1]
	v_add_f32_dpp v80, v79, v79 row_half_mirror row_mask:0xf bank_mask:0xf bound_ctrl:1
	ds_read_b32 v36, v11 offset:44288
	ds_read_b32 v37, v12 offset:44288
	v_pk_fma_f32 v[72:73], v[6:7], v[50:51], v[72:73] op_sel_hi:[1,0,1]
	v_add_f32_dpp v76, v80, v80 row_mirror row_mask:0xf bank_mask:0xf bound_ctrl:1
	ds_read_b64 v[38:39], v13 offset:45264
	v_pk_fma_f32 v[74:75], v[8:9], v[50:51], v[74:75] op_sel:[0,1,0] op_sel_hi:[1,1,1]
	v_mul_f32_e32 v83, v60, v62
	v_mov_b32_dpp v77, v76 quad_perm:[1,0,3,2] row_mask:0xf bank_mask:0xf bound_ctrl:1
	v_add_f32_dpp v81, v67, v66 quad_perm:[1,0,3,2] row_mask:0xf bank_mask:0xf bound_ctrl:1
	v_pk_fma_f32 v[2:3], v[56:57], v[76:77], v[68:69] op_sel_hi:[0,1,1] neg_lo:[1,0,0] neg_hi:[1,0,0]
	v_pk_fma_f32 v[4:5], v[56:57], v[76:77], v[70:71] op_sel:[1,0,0] op_sel_hi:[1,1,1] neg_lo:[1,0,0] neg_hi:[1,0,0]
	v_pk_fma_f32 v[6:7], v[58:59], v[76:77], v[72:73] op_sel_hi:[0,1,1] neg_lo:[1,0,0] neg_hi:[1,0,0]
	v_pk_fma_f32 v[8:9], v[58:59], v[76:77], v[74:75] op_sel:[1,0,0] op_sel_hi:[1,1,1] neg_lo:[1,0,0] neg_hi:[1,0,0]
	v_fma_f32 v83, -v76, v63, v83
	v_add_f32_dpp v82, v81, v81 quad_perm:[3,2,1,0] row_mask:0xf bank_mask:0xf bound_ctrl:1
	v_fmac_f32_e32 v82, 0x3e800000, v83
	ds_write_b32 v14, v82 offset:12800
	s_waitcnt lgkmcnt(1)
; #define LAS __attribute__((address_space(3)))
; template <int CTRL> __device__ __forceinline__ float dppf(float x) { return __builtin_bit_cast(float, __builtin_amdgcn_mov_dpp(__builtin_bit_cast(int, x), CTRL, 0xf, 0xf, true)); }
; __device__ __forceinline__ float sum16(float x) { x = sum8(x); x += dppf<0x140>(x); return x; }
; __device__ __forceinline__ void rwkv_item(LAS unsigned char* lds, int l, const bf16_t* PROJ, const bf16_t* LO, bf16_t* YR, float* BON, int b, int h, int qv) {
;     ...
;             for (int t = 0; t < CH; ++t) {
;                 const int tn = (t + 1) & (CH - 1);
;                 const LAS float* pn = pk + tn * 64;
;                 const f32x4 nkk = *(const LAS f32x4*)(pn), nwr = *(const LAS f32x4*)(pn + 2048), nw = *(const LAS f32x4*)(pn + 4096), nk = *(const LAS f32x4*)(pn + 6144), na = *(const LAS f32x4*)(pn + 8192);
;                 const float nv0 = pv[tn * 32], nv1 = pv[tn * 32 + 4]; const f32x2 nsc = *(const LAS f32x2*)(ps + 2 * tn);
;                 float sa[2], yp[2];
; #pragma unroll
;                 for (int c = 0; c < 2; ++c) { const f32x2 pa = S23[c] * kk4.hi + S01[c] * kk4.lo, pb = S23[c] * wr4.hi + S01[c] * wr4.lo; sa[c] = pa.x + pa.y; yp[c] = pb.x + pb.y; }
; #pragma unroll
;                 for (int c = 0; c < 2; ++c) { sa[c] = sum16(sa[c]); yp[c] += dppf<0xB1>(yp[c]); yp[c] += dppf<0x4E>(yp[c]); }
; #pragma unroll
;                 for (int c = 0; c < 2; ++c) {
;                     S01[c] = S01[c] * w4.lo + (k4.lo * vv[c] - a4.lo * sa[c]);
;                     S23[c] = S23[c] * w4.hi + (k4.hi * vv[c] - a4.hi * sa[c]);
;                     py[(t * 32 + 4 * c) * 4] = yp[c] + 0.25f * (vv[c] * sc.x - sa[c] * sc.y);
;                 }
;                 kk4 = nkk; wr4 = nwr; w4 = nw; k4 = nk; a4 = na; vv[0] = nv0; vv[1] = nv1; sc = nsc;
;             }
	v_pk_mul_f32 v[64:65], v[2:3], v[16:17] op_sel_hi:[1,0]
	v_pk_mul_f32 v[66:67], v[2:3], v[20:21] op_sel_hi:[1,0]
	v_pk_mul_f32 v[68:69], v[36:37], v[28:29] op_sel_hi:[1,0]
	v_pk_fma_f32 v[64:65], v[4:5], v[16:17], v[64:65] op_sel:[0,1,0] op_sel_hi:[1,1,1]
	v_pk_fma_f32 v[66:67], v[4:5], v[20:21], v[66:67] op_sel:[0,1,0] op_sel_hi:[1,1,1]
	v_pk_mul_f32 v[70:71], v[36:37], v[28:29] op_sel:[0,1] op_sel_hi:[1,1]
	v_pk_fma_f32 v[64:65], v[6:7], v[18:19], v[64:65] op_sel_hi:[1,0,1]
	v_pk_fma_f32 v[66:67], v[6:7], v[22:23], v[66:67] op_sel_hi:[1,0,1]
	v_pk_mul_f32 v[72:73], v[36:37], v[30:31] op_sel_hi:[1,0]
	v_pk_fma_f32 v[64:65], v[8:9], v[18:19], v[64:65] op_sel:[0,1,0] op_sel_hi:[1,1,1]
	v_pk_fma_f32 v[66:67], v[8:9], v[22:23], v[66:67] op_sel:[0,1,0] op_sel_hi:[1,1,1]
	v_pk_mul_f32 v[74:75], v[36:37], v[30:31] op_sel:[0,1] op_sel_hi:[1,1]
	ds_read_b128 v[40:43], v10 offset:6912
	v_add_f32_dpp v78, v65, v64 quad_perm:[1,0,3,2] row_mask:0xf bank_mask:0xf bound_ctrl:1
	ds_read_b128 v[44:47], v10 offset:15104
	ds_read_b128 v[48:51], v10 offset:23296
	v_pk_fma_f32 v[68:69], v[2:3], v[24:25], v[68:69] op_sel_hi:[1,0,1]
	v_add_f32_dpp v79, v78, v78 quad_perm:[3,2,1,0] row_mask:0xf bank_mask:0xf bound_ctrl:1
	ds_read_b128 v[52:55], v10 offset:31488
	ds_read_b128 v[56:59], v10 offset:39680
	v_pk_fma_f32 v[70:71], v[4:5], v[24:25], v[70:71] op_sel:[0,1,0] op_sel_hi:[1,1,1]
	v_add_f32_dpp v80, v79, v79 row_half_mirror row_mask:0xf bank_mask:0xf bound_ctrl:1
	ds_read_b32 v60, v11 offset:44416
	ds_read_b32 v61, v12 offset:44416
	v_pk_fma_f32 v[72:73], v[6:7], v[26:27], v[72:73] op_sel_hi:[1,0,1]
	v_add_f32_dpp v76, v80, v80 row_mirror row_mask:0xf bank_mask:0xf bound_ctrl:1
	ds_read_b64 v[62:63], v13 offset:45272
	v_pk_fma_f32 v[74:75], v[8:9], v[26:27], v[74:75] op_sel:[0,1,0] op_sel_hi:[1,1,1]
	v_mul_f32_e32 v83, v36, v38
	v_mov_b32_dpp v77, v76 quad_perm:[1,0,3,2] row_mask:0xf bank_mask:0xf bound_ctrl:1
	v_add_f32_dpp v81, v67, v66 quad_perm:[1,0,3,2] row_mask:0xf bank_mask:0xf bound_ctrl:1
	v_pk_fma_f32 v[2:3], v[32:33], v[76:77], v[68:69] op_sel_hi:[0,1,1] neg_lo:[1,0,0] neg_hi:[1,0,0]
	v_pk_fma_f32 v[4:5], v[32:33], v[76:77], v[70:71] op_sel:[1,0,0] op_sel_hi:[1,1,1] neg_lo:[1,0,0] neg_hi:[1,0,0]
	v_pk_fma_f32 v[6:7], v[34:35], v[76:77], v[72:73] op_sel_hi:[0,1,1] neg_lo:[1,0,0] neg_hi:[1,0,0]
	v_pk_fma_f32 v[8:9], v[34:35], v[76:77], v[74:75] op_sel:[1,0,0] op_sel_hi:[1,1,1] neg_lo:[1,0,0] neg_hi:[1,0,0]
	v_fma_f32 v83, -v76, v39, v83
	v_add_f32_dpp v82, v81, v81 quad_perm:[3,2,1,0] row_mask:0xf bank_mask:0xf bound_ctrl:1
	v_fmac_f32_e32 v82, 0x3e800000, v83
	ds_write_b32 v14, v82 offset:13312
	s_waitcnt lgkmcnt(1)
	v_pk_mul_f32 v[64:65], v[2:3], v[40:41] op_sel_hi:[1,0]
	v_pk_mul_f32 v[66:67], v[2:3], v[44:45] op_sel_hi:[1,0]
	v_pk_mul_f32 v[68:69], v[60:61], v[52:53] op_sel_hi:[1,0]
	v_pk_fma_f32 v[64:65], v[4:5], v[40:41], v[64:65] op_sel:[0,1,0] op_sel_hi:[1,1,1]
	v_pk_fma_f32 v[66:67], v[4:5], v[44:45], v[66:67] op_sel:[0,1,0] op_sel_hi:[1,1,1]
	v_pk_mul_f32 v[70:71], v[60:61], v[52:53] op_sel:[0,1] op_sel_hi:[1,1]
	v_pk_fma_f32 v[64:65], v[6:7], v[42:43], v[64:65] op_sel_hi:[1,0,1]
	v_pk_fma_f32 v[66:67], v[6:7], v[46:47], v[66:67] op_sel_hi:[1,0,1]
	v_pk_mul_f32 v[72:73], v[60:61], v[54:55] op_sel_hi:[1,0]
	v_pk_fma_f32 v[64:65], v[8:9], v[42:43], v[64:65] op_sel:[0,1,0] op_sel_hi:[1,1,1]
	v_pk_fma_f32 v[66:67], v[8:9], v[46:47], v[66:67] op_sel:[0,1,0] op_sel_hi:[1,1,1]
	v_pk_mul_f32 v[74:75], v[60:61], v[54:55] op_sel:[0,1] op_sel_hi:[1,1]
	ds_read_b128 v[16:19], v10 offset:7168
	v_add_f32_dpp v78, v65, v64 quad_perm:[1,0,3,2] row_mask:0xf bank_mask:0xf bound_ctrl:1
	ds_read_b128 v[20:23], v10 offset:15360
	ds_read_b128 v[24:27], v10 offset:23552
	v_pk_fma_f32 v[68:69], v[2:3], v[48:49], v[68:69] op_sel_hi:[1,0,1]
	v_add_f32_dpp v79, v78, v78 quad_perm:[3,2,1,0] row_mask:0xf bank_mask:0xf bound_ctrl:1
	ds_read_b128 v[28:31], v10 offset:31744
	ds_read_b128 v[32:35], v10 offset:39936
	v_pk_fma_f32 v[70:71], v[4:5], v[48:49], v[70:71] op_sel:[0,1,0] op_sel_hi:[1,1,1]
	v_add_f32_dpp v80, v79, v79 row_half_mirror row_mask:0xf bank_mask:0xf bound_ctrl:1
	ds_read_b32 v36, v11 offset:44544
	ds_read_b32 v37, v12 offset:44544
	v_pk_fma_f32 v[72:73], v[6:7], v[50:51], v[72:73] op_sel_hi:[1,0,1]
	v_add_f32_dpp v76, v80, v80 row_mirror row_mask:0xf bank_mask:0xf bound_ctrl:1
	ds_read_b64 v[38:39], v13 offset:45280
	v_pk_fma_f32 v[74:75], v[8:9], v[50:51], v[74:75] op_sel:[0,1,0] op_sel_hi:[1,1,1]
	v_mul_f32_e32 v83, v60, v62
	v_mov_b32_dpp v77, v76 quad_perm:[1,0,3,2] row_mask:0xf bank_mask:0xf bound_ctrl:1
	v_add_f32_dpp v81, v67, v66 quad_perm:[1,0,3,2] row_mask:0xf bank_mask:0xf bound_ctrl:1
	v_pk_fma_f32 v[2:3], v[56:57], v[76:77], v[68:69] op_sel_hi:[0,1,1] neg_lo:[1,0,0] neg_hi:[1,0,0]
	v_pk_fma_f32 v[4:5], v[56:57], v[76:77], v[70:71] op_sel:[1,0,0] op_sel_hi:[1,1,1] neg_lo:[1,0,0] neg_hi:[1,0,0]
	v_pk_fma_f32 v[6:7], v[58:59], v[76:77], v[72:73] op_sel_hi:[0,1,1] neg_lo:[1,0,0] neg_hi:[1,0,0]
	v_pk_fma_f32 v[8:9], v[58:59], v[76:77], v[74:75] op_sel:[1,0,0] op_sel_hi:[1,1,1] neg_lo:[1,0,0] neg_hi:[1,0,0]
	v_fma_f32 v83, -v76, v63, v83
	v_add_f32_dpp v82, v81, v81 quad_perm:[3,2,1,0] row_mask:0xf bank_mask:0xf bound_ctrl:1
	v_fmac_f32_e32 v82, 0x3e800000, v83
	ds_write_b32 v14, v82 offset:13824
	s_waitcnt lgkmcnt(1)
; #define LAS __attribute__((address_space(3)))
; template <int CTRL> __device__ __forceinline__ float dppf(float x) { return __builtin_bit_cast(float, __builtin_amdgcn_mov_dpp(__builtin_bit_cast(int, x), CTRL, 0xf, 0xf, true)); }
; __device__ __forceinline__ float sum16(float x) { x = sum8(x); x += dppf<0x140>(x); return x; }
; __device__ __forceinline__ void rwkv_item(LAS unsigned char* lds, int l, const bf16_t* PROJ, const bf16_t* LO, bf16_t* YR, float* BON, int b, int h, int qv) {
;     ...
;             for (int t = 0; t < CH; ++t) {
;                 const int tn = (t + 1) & (CH - 1);
;                 const LAS float* pn = pk + tn * 64;
;                 const f32x4 nkk = *(const LAS f32x4*)(pn), nwr = *(const LAS f32x4*)(pn + 2048), nw = *(const LAS f32x4*)(pn + 4096), nk = *(const LAS f32x4*)(pn + 6144), na = *(const LAS f32x4*)(pn + 8192);
;                 const float nv0 = pv[tn * 32], nv1 = pv[tn * 32 + 4]; const f32x2 nsc = *(const LAS f32x2*)(ps + 2 * tn);
;                 float sa[2], yp[2];
; #pragma unroll
;                 for (int c = 0; c < 2; ++c) { const f32x2 pa = S23[c] * kk4.hi + S01[c] * kk4.lo, pb = S23[c] * wr4.hi + S01[c] * wr4.lo; sa[c] = pa.x + pa.y; yp[c] = pb.x + pb.y; }
; #pragma unroll
;                 for (int c = 0; c < 2; ++c) { sa[c] = sum16(sa[c]); yp[c] += dppf<0xB1>(yp[c]); yp[c] += dppf<0x4E>(yp[c]); }
; #pragma unroll
;                 for (int c = 0; c < 2; ++c) {
;                     S01[c] = S01[c] * w4.lo + (k4.lo * vv[c] - a4.lo * sa[c]);
;                     S23[c] = S23[c] * w4.hi + (k4.hi * vv[c] - a4.hi * sa[c]);
;                     py[(t * 32 + 4 * c) * 4] = yp[c] + 0.25f * (vv[c] * sc.x - sa[c] * sc.y);
;                 }
;                 kk4 = nkk; wr4 = nwr; w4 = nw; k4 = nk; a4 = na; vv[0] = nv0; vv[1] = nv1; sc = nsc;
;             }
	v_pk_mul_f32 v[64:65], v[2:3], v[16:17] op_sel_hi:[1,0]
	v_pk_mul_f32 v[66:67], v[2:3], v[20:21] op_sel_hi:[1,0]
	v_pk_mul_f32 v[68:69], v[36:37], v[28:29] op_sel_hi:[1,0]
	v_pk_fma_f32 v[64:65], v[4:5], v[16:17], v[64:65] op_sel:[0,1,0] op_sel_hi:[1,1,1]
	v_pk_fma_f32 v[66:67], v[4:5], v[20:21], v[66:67] op_sel:[0,1,0] op_sel_hi:[1,1,1]
	v_pk_mul_f32 v[70:71], v[36:37], v[28:29] op_sel:[0,1] op_sel_hi:[1,1]
	v_pk_fma_f32 v[64:65], v[6:7], v[18:19], v[64:65] op_sel_hi:[1,0,1]
	v_pk_fma_f32 v[66:67], v[6:7], v[22:23], v[66:67] op_sel_hi:[1,0,1]
	v_pk_mul_f32 v[72:73], v[36:37], v[30:31] op_sel_hi:[1,0]
	v_pk_fma_f32 v[64:65], v[8:9], v[18:19], v[64:65] op_sel:[0,1,0] op_sel_hi:[1,1,1]
	v_pk_fma_f32 v[66:67], v[8:9], v[22:23], v[66:67] op_sel:[0,1,0] op_sel_hi:[1,1,1]
	v_pk_mul_f32 v[74:75], v[36:37], v[30:31] op_sel:[0,1] op_sel_hi:[1,1]
	ds_read_b128 v[40:43], v10 offset:7424
	v_add_f32_dpp v78, v65, v64 quad_perm:[1,0,3,2] row_mask:0xf bank_mask:0xf bound_ctrl:1
	ds_read_b128 v[44:47], v10 offset:15616
	ds_read_b128 v[48:51], v10 offset:23808
	v_pk_fma_f32 v[68:69], v[2:3], v[24:25], v[68:69] op_sel_hi:[1,0,1]
	v_add_f32_dpp v79, v78, v78 quad_perm:[3,2,1,0] row_mask:0xf bank_mask:0xf bound_ctrl:1
	ds_read_b128 v[52:55], v10 offset:32000
	ds_read_b128 v[56:59], v10 offset:40192
	v_pk_fma_f32 v[70:71], v[4:5], v[24:25], v[70:71] op_sel:[0,1,0] op_sel_hi:[1,1,1]
	v_add_f32_dpp v80, v79, v79 row_half_mirror row_mask:0xf bank_mask:0xf bound_ctrl:1
	ds_read_b32 v60, v11 offset:44672
	ds_read_b32 v61, v12 offset:44672
	v_pk_fma_f32 v[72:73], v[6:7], v[26:27], v[72:73] op_sel_hi:[1,0,1]
	v_add_f32_dpp v76, v80, v80 row_mirror row_mask:0xf bank_mask:0xf bound_ctrl:1
	ds_read_b64 v[62:63], v13 offset:45288
	v_pk_fma_f32 v[74:75], v[8:9], v[26:27], v[74:75] op_sel:[0,1,0] op_sel_hi:[1,1,1]
	v_mul_f32_e32 v83, v36, v38
	v_mov_b32_dpp v77, v76 quad_perm:[1,0,3,2] row_mask:0xf bank_mask:0xf bound_ctrl:1
	v_add_f32_dpp v81, v67, v66 quad_perm:[1,0,3,2] row_mask:0xf bank_mask:0xf bound_ctrl:1
	v_pk_fma_f32 v[2:3], v[32:33], v[76:77], v[68:69] op_sel_hi:[0,1,1] neg_lo:[1,0,0] neg_hi:[1,0,0]
	v_pk_fma_f32 v[4:5], v[32:33], v[76:77], v[70:71] op_sel:[1,0,0] op_sel_hi:[1,1,1] neg_lo:[1,0,0] neg_hi:[1,0,0]
	v_pk_fma_f32 v[6:7], v[34:35], v[76:77], v[72:73] op_sel_hi:[0,1,1] neg_lo:[1,0,0] neg_hi:[1,0,0]
	v_pk_fma_f32 v[8:9], v[34:35], v[76:77], v[74:75] op_sel:[1,0,0] op_sel_hi:[1,1,1] neg_lo:[1,0,0] neg_hi:[1,0,0]
	v_fma_f32 v83, -v76, v39, v83
	v_add_f32_dpp v82, v81, v81 quad_perm:[3,2,1,0] row_mask:0xf bank_mask:0xf bound_ctrl:1
	v_fmac_f32_e32 v82, 0x3e800000, v83
	ds_write_b32 v14, v82 offset:14336
	s_waitcnt lgkmcnt(1)
	v_pk_mul_f32 v[64:65], v[2:3], v[40:41] op_sel_hi:[1,0]
	v_pk_mul_f32 v[66:67], v[2:3], v[44:45] op_sel_hi:[1,0]
	v_pk_mul_f32 v[68:69], v[60:61], v[52:53] op_sel_hi:[1,0]
	v_pk_fma_f32 v[64:65], v[4:5], v[40:41], v[64:65] op_sel:[0,1,0] op_sel_hi:[1,1,1]
	v_pk_fma_f32 v[66:67], v[4:5], v[44:45], v[66:67] op_sel:[0,1,0] op_sel_hi:[1,1,1]
	v_pk_mul_f32 v[70:71], v[60:61], v[52:53] op_sel:[0,1] op_sel_hi:[1,1]
	v_pk_fma_f32 v[64:65], v[6:7], v[42:43], v[64:65] op_sel_hi:[1,0,1]
	v_pk_fma_f32 v[66:67], v[6:7], v[46:47], v[66:67] op_sel_hi:[1,0,1]
	v_pk_mul_f32 v[72:73], v[60:61], v[54:55] op_sel_hi:[1,0]
	v_pk_fma_f32 v[64:65], v[8:9], v[42:43], v[64:65] op_sel:[0,1,0] op_sel_hi:[1,1,1]
	v_pk_fma_f32 v[66:67], v[8:9], v[46:47], v[66:67] op_sel:[0,1,0] op_sel_hi:[1,1,1]
	v_pk_mul_f32 v[74:75], v[60:61], v[54:55] op_sel:[0,1] op_sel_hi:[1,1]
	ds_read_b128 v[16:19], v10 offset:7680
	v_add_f32_dpp v78, v65, v64 quad_perm:[1,0,3,2] row_mask:0xf bank_mask:0xf bound_ctrl:1
	ds_read_b128 v[20:23], v10 offset:15872
	ds_read_b128 v[24:27], v10 offset:24064
	v_pk_fma_f32 v[68:69], v[2:3], v[48:49], v[68:69] op_sel_hi:[1,0,1]
	v_add_f32_dpp v79, v78, v78 quad_perm:[3,2,1,0] row_mask:0xf bank_mask:0xf bound_ctrl:1
	ds_read_b128 v[28:31], v10 offset:32256
	ds_read_b128 v[32:35], v10 offset:40448
	v_pk_fma_f32 v[70:71], v[4:5], v[48:49], v[70:71] op_sel:[0,1,0] op_sel_hi:[1,1,1]
	v_add_f32_dpp v80, v79, v79 row_half_mirror row_mask:0xf bank_mask:0xf bound_ctrl:1
	ds_read_b32 v36, v11 offset:44800
	ds_read_b32 v37, v12 offset:44800
	v_pk_fma_f32 v[72:73], v[6:7], v[50:51], v[72:73] op_sel_hi:[1,0,1]
	v_add_f32_dpp v76, v80, v80 row_mirror row_mask:0xf bank_mask:0xf bound_ctrl:1
	ds_read_b64 v[38:39], v13 offset:45296
	v_pk_fma_f32 v[74:75], v[8:9], v[50:51], v[74:75] op_sel:[0,1,0] op_sel_hi:[1,1,1]
	v_mul_f32_e32 v83, v60, v62
	v_mov_b32_dpp v77, v76 quad_perm:[1,0,3,2] row_mask:0xf bank_mask:0xf bound_ctrl:1
	v_add_f32_dpp v81, v67, v66 quad_perm:[1,0,3,2] row_mask:0xf bank_mask:0xf bound_ctrl:1
	v_pk_fma_f32 v[2:3], v[56:57], v[76:77], v[68:69] op_sel_hi:[0,1,1] neg_lo:[1,0,0] neg_hi:[1,0,0]
	v_pk_fma_f32 v[4:5], v[56:57], v[76:77], v[70:71] op_sel:[1,0,0] op_sel_hi:[1,1,1] neg_lo:[1,0,0] neg_hi:[1,0,0]
	v_pk_fma_f32 v[6:7], v[58:59], v[76:77], v[72:73] op_sel_hi:[0,1,1] neg_lo:[1,0,0] neg_hi:[1,0,0]
	v_pk_fma_f32 v[8:9], v[58:59], v[76:77], v[74:75] op_sel:[1,0,0] op_sel_hi:[1,1,1] neg_lo:[1,0,0] neg_hi:[1,0,0]
	v_fma_f32 v83, -v76, v63, v83
	v_add_f32_dpp v82, v81, v81 quad_perm:[3,2,1,0] row_mask:0xf bank_mask:0xf bound_ctrl:1
	v_fmac_f32_e32 v82, 0x3e800000, v83
	ds_write_b32 v14, v82 offset:14848
	s_waitcnt lgkmcnt(1)
; #define LAS __attribute__((address_space(3)))
; template <int CTRL> __device__ __forceinline__ float dppf(float x) { return __builtin_bit_cast(float, __builtin_amdgcn_mov_dpp(__builtin_bit_cast(int, x), CTRL, 0xf, 0xf, true)); }
; __device__ __forceinline__ float sum16(float x) { x = sum8(x); x += dppf<0x140>(x); return x; }
; __device__ __forceinline__ void rwkv_item(LAS unsigned char* lds, int l, const bf16_t* PROJ, const bf16_t* LO, bf16_t* YR, float* BON, int b, int h, int qv) {
;     ...
;             for (int t = 0; t < CH; ++t) {
;                 const int tn = (t + 1) & (CH - 1);
;                 const LAS float* pn = pk + tn * 64;
;                 const f32x4 nkk = *(const LAS f32x4*)(pn), nwr = *(const LAS f32x4*)(pn + 2048), nw = *(const LAS f32x4*)(pn + 4096), nk = *(const LAS f32x4*)(pn + 6144), na = *(const LAS f32x4*)(pn + 8192);
;                 const float nv0 = pv[tn * 32], nv1 = pv[tn * 32 + 4]; const f32x2 nsc = *(const LAS f32x2*)(ps + 2 * tn);
;                 float sa[2], yp[2];
; #pragma unroll
;                 for (int c = 0; c < 2; ++c) { const f32x2 pa = S23[c] * kk4.hi + S01[c] * kk4.lo, pb = S23[c] * wr4.hi + S01[c] * wr4.lo; sa[c] = pa.x + pa.y; yp[c] = pb.x + pb.y; }
; #pragma unroll
;                 for (int c = 0; c < 2; ++c) { sa[c] = sum16(sa[c]); yp[c] += dppf<0xB1>(yp[c]); yp[c] += dppf<0x4E>(yp[c]); }
; #pragma unroll
;                 for (int c = 0; c < 2; ++c) {
;                     S01[c] = S01[c] * w4.lo + (k4.lo * vv[c] - a4.lo * sa[c]);
;                     S23[c] = S23[c] * w4.hi + (k4.hi * vv[c] - a4.hi * sa[c]);
;                     py[(t * 32 + 4 * c) * 4] = yp[c] + 0.25f * (vv[c] * sc.x - sa[c] * sc.y);
;                 }
;                 kk4 = nkk; wr4 = nwr; w4 = nw; k4 = nk; a4 = na; vv[0] = nv0; vv[1] = nv1; sc = nsc;
;             }
;             __syncthreads();
	v_pk_mul_f32 v[64:65], v[2:3], v[16:17] op_sel_hi:[1,0]
	v_pk_mul_f32 v[66:67], v[2:3], v[20:21] op_sel_hi:[1,0]
	v_pk_mul_f32 v[68:69], v[36:37], v[28:29] op_sel_hi:[1,0]
	v_pk_fma_f32 v[64:65], v[4:5], v[16:17], v[64:65] op_sel:[0,1,0] op_sel_hi:[1,1,1]
	v_pk_fma_f32 v[66:67], v[4:5], v[20:21], v[66:67] op_sel:[0,1,0] op_sel_hi:[1,1,1]
	v_pk_mul_f32 v[70:71], v[36:37], v[28:29] op_sel:[0,1] op_sel_hi:[1,1]
	v_pk_fma_f32 v[64:65], v[6:7], v[18:19], v[64:65] op_sel_hi:[1,0,1]
	v_pk_fma_f32 v[66:67], v[6:7], v[22:23], v[66:67] op_sel_hi:[1,0,1]
	v_pk_mul_f32 v[72:73], v[36:37], v[30:31] op_sel_hi:[1,0]
	v_pk_fma_f32 v[64:65], v[8:9], v[18:19], v[64:65] op_sel:[0,1,0] op_sel_hi:[1,1,1]
	v_pk_fma_f32 v[66:67], v[8:9], v[22:23], v[66:67] op_sel:[0,1,0] op_sel_hi:[1,1,1]
	v_pk_mul_f32 v[74:75], v[36:37], v[30:31] op_sel:[0,1] op_sel_hi:[1,1]
	ds_read_b128 v[40:43], v10 offset:7936
	v_add_f32_dpp v78, v65, v64 quad_perm:[1,0,3,2] row_mask:0xf bank_mask:0xf bound_ctrl:1
	ds_read_b128 v[44:47], v10 offset:16128
	ds_read_b128 v[48:51], v10 offset:24320
	v_pk_fma_f32 v[68:69], v[2:3], v[24:25], v[68:69] op_sel_hi:[1,0,1]
	v_add_f32_dpp v79, v78, v78 quad_perm:[3,2,1,0] row_mask:0xf bank_mask:0xf bound_ctrl:1
	ds_read_b128 v[52:55], v10 offset:32512
	ds_read_b128 v[56:59], v10 offset:40704
	v_pk_fma_f32 v[70:71], v[4:5], v[24:25], v[70:71] op_sel:[0,1,0] op_sel_hi:[1,1,1]
	v_add_f32_dpp v80, v79, v79 row_half_mirror row_mask:0xf bank_mask:0xf bound_ctrl:1
	ds_read_b32 v60, v11 offset:44928
	ds_read_b32 v61, v12 offset:44928
	v_pk_fma_f32 v[72:73], v[6:7], v[26:27], v[72:73] op_sel_hi:[1,0,1]
	v_add_f32_dpp v76, v80, v80 row_mirror row_mask:0xf bank_mask:0xf bound_ctrl:1
	ds_read_b64 v[62:63], v13 offset:45304
	v_pk_fma_f32 v[74:75], v[8:9], v[26:27], v[74:75] op_sel:[0,1,0] op_sel_hi:[1,1,1]
	v_mul_f32_e32 v83, v36, v38
	v_mov_b32_dpp v77, v76 quad_perm:[1,0,3,2] row_mask:0xf bank_mask:0xf bound_ctrl:1
	v_add_f32_dpp v81, v67, v66 quad_perm:[1,0,3,2] row_mask:0xf bank_mask:0xf bound_ctrl:1
	v_pk_fma_f32 v[2:3], v[32:33], v[76:77], v[68:69] op_sel_hi:[0,1,1] neg_lo:[1,0,0] neg_hi:[1,0,0]
	v_pk_fma_f32 v[4:5], v[32:33], v[76:77], v[70:71] op_sel:[1,0,0] op_sel_hi:[1,1,1] neg_lo:[1,0,0] neg_hi:[1,0,0]
	v_pk_fma_f32 v[6:7], v[34:35], v[76:77], v[72:73] op_sel_hi:[0,1,1] neg_lo:[1,0,0] neg_hi:[1,0,0]
	v_pk_fma_f32 v[8:9], v[34:35], v[76:77], v[74:75] op_sel:[1,0,0] op_sel_hi:[1,1,1] neg_lo:[1,0,0] neg_hi:[1,0,0]
	v_fma_f32 v83, -v76, v39, v83
	v_add_f32_dpp v82, v81, v81 quad_perm:[3,2,1,0] row_mask:0xf bank_mask:0xf bound_ctrl:1
	v_fmac_f32_e32 v82, 0x3e800000, v83
	ds_write_b32 v14, v82 offset:15360
	s_waitcnt lgkmcnt(1)
	v_pk_mul_f32 v[64:65], v[2:3], v[40:41] op_sel_hi:[1,0]
	v_pk_mul_f32 v[66:67], v[2:3], v[44:45] op_sel_hi:[1,0]
	v_pk_mul_f32 v[68:69], v[60:61], v[52:53] op_sel_hi:[1,0]
	v_pk_fma_f32 v[64:65], v[4:5], v[40:41], v[64:65] op_sel:[0,1,0] op_sel_hi:[1,1,1]
	v_pk_fma_f32 v[66:67], v[4:5], v[44:45], v[66:67] op_sel:[0,1,0] op_sel_hi:[1,1,1]
	v_pk_mul_f32 v[70:71], v[60:61], v[52:53] op_sel:[0,1] op_sel_hi:[1,1]
	v_pk_fma_f32 v[64:65], v[6:7], v[42:43], v[64:65] op_sel_hi:[1,0,1]
	v_pk_fma_f32 v[66:67], v[6:7], v[46:47], v[66:67] op_sel_hi:[1,0,1]
	v_pk_mul_f32 v[72:73], v[60:61], v[54:55] op_sel_hi:[1,0]
	v_pk_fma_f32 v[64:65], v[8:9], v[42:43], v[64:65] op_sel:[0,1,0] op_sel_hi:[1,1,1]
	v_pk_fma_f32 v[66:67], v[8:9], v[46:47], v[66:67] op_sel:[0,1,0] op_sel_hi:[1,1,1]
	v_pk_mul_f32 v[74:75], v[60:61], v[54:55] op_sel:[0,1] op_sel_hi:[1,1]
	s_nop 0
	v_add_f32_dpp v78, v65, v64 quad_perm:[1,0,3,2] row_mask:0xf bank_mask:0xf bound_ctrl:1
	s_nop 0
	s_nop 0
	v_pk_fma_f32 v[68:69], v[2:3], v[48:49], v[68:69] op_sel_hi:[1,0,1]
	v_add_f32_dpp v79, v78, v78 quad_perm:[3,2,1,0] row_mask:0xf bank_mask:0xf bound_ctrl:1
	s_nop 0
	s_nop 0
	v_pk_fma_f32 v[70:71], v[4:5], v[48:49], v[70:71] op_sel:[0,1,0] op_sel_hi:[1,1,1]
	v_add_f32_dpp v80, v79, v79 row_half_mirror row_mask:0xf bank_mask:0xf bound_ctrl:1
	s_nop 0
	s_nop 0
	v_pk_fma_f32 v[72:73], v[6:7], v[50:51], v[72:73] op_sel_hi:[1,0,1]
	v_add_f32_dpp v76, v80, v80 row_mirror row_mask:0xf bank_mask:0xf bound_ctrl:1
	s_nop 0
	v_pk_fma_f32 v[74:75], v[8:9], v[50:51], v[74:75] op_sel:[0,1,0] op_sel_hi:[1,1,1]
	v_mul_f32_e32 v83, v60, v62
	v_mov_b32_dpp v77, v76 quad_perm:[1,0,3,2] row_mask:0xf bank_mask:0xf bound_ctrl:1
	v_add_f32_dpp v81, v67, v66 quad_perm:[1,0,3,2] row_mask:0xf bank_mask:0xf bound_ctrl:1
	v_pk_fma_f32 v[2:3], v[56:57], v[76:77], v[68:69] op_sel_hi:[0,1,1] neg_lo:[1,0,0] neg_hi:[1,0,0]
	v_pk_fma_f32 v[4:5], v[56:57], v[76:77], v[70:71] op_sel:[1,0,0] op_sel_hi:[1,1,1] neg_lo:[1,0,0] neg_hi:[1,0,0]
	v_pk_fma_f32 v[6:7], v[58:59], v[76:77], v[72:73] op_sel_hi:[0,1,1] neg_lo:[1,0,0] neg_hi:[1,0,0]
	v_pk_fma_f32 v[8:9], v[58:59], v[76:77], v[74:75] op_sel:[1,0,0] op_sel_hi:[1,1,1] neg_lo:[1,0,0] neg_hi:[1,0,0]
	v_fma_f32 v83, -v76, v63, v83
	v_add_f32_dpp v82, v81, v81 quad_perm:[3,2,1,0] row_mask:0xf bank_mask:0xf bound_ctrl:1
	v_fmac_f32_e32 v82, 0x3e800000, v83
	ds_write_b32 v14, v82 offset:15872
	s_add_i32 s30, s30, 1
	s_cmpk_eq_i32 s30, 0x80
	s_waitcnt lgkmcnt(0)
	s_barrier
	s_cbranch_scc0 .Lscan_chunk
	s_setprio 0
	s_mov_b64 s[30:31], 0
